# grid barrier: XCD leader no longer waits for the completion of its own TOPGEN/XGEN atomic adds before leaving the barrier
# speedup vs baseline: 1.0176x; 1.0045x over previous
.LBB0_196:
	s_or_b64 exec, exec, s[8:9]
	s_mov_b64 s[8:9], exec
	v_mbcnt_lo_u32_b32 v0, s8, 0
	v_mbcnt_hi_u32_b32 v0, s9, v0
	v_cmp_eq_u32_e32 vcc, 0, v0
	s_and_saveexec_b64 s[10:11], vcc
	s_cbranch_execz .LBB0_198
	s_bcnt1_i32_b64 s3, s[8:9]
	v_mov_b32_e32 v0, 0x2000
	v_mov_b32_e32 v1, s3
	global_atomic_add v0, v1, s[6:7] offset:1024
.LBB0_198:
	s_or_b64 exec, exec, s[10:11]
.LBB0_199:
	s_or_b64 exec, exec, s[4:5]
	s_load_dwordx16 s[4:19], s[0:1], 0x100
	s_load_dwordx16 s[56:71], s[0:1], 0x1c0
	s_lshr_b32 s93, s38, 3
	s_and_b32 s94, s2, 7
	s_lshr_b32 s95, s2, 3
	s_waitcnt lgkmcnt(0)
	v_writelane_b32 v254, s4, 52
	s_mul_i32 s0, s93, s94
	s_add_i32 s96, s95, s0
	v_writelane_b32 v254, s5, 53
	v_writelane_b32 v254, s6, 54
	v_writelane_b32 v254, s7, 55
	v_writelane_b32 v254, s8, 56
	v_writelane_b32 v254, s9, 57
	v_writelane_b32 v254, s10, 58
	v_writelane_b32 v254, s11, 59
	v_writelane_b32 v254, s12, 60
	v_writelane_b32 v255, s16, 0
	v_writelane_b32 v254, s13, 61
	v_writelane_b32 v255, s17, 1
	v_writelane_b32 v254, s14, 62
	v_writelane_b32 v255, s18, 2
	s_lshl_b32 s0, s96, 8
	v_writelane_b32 v254, s15, 63
	v_writelane_b32 v255, s19, 3
	s_add_i32 s3, s96, 0xfffffe74
	s_and_b32 s97, s38, -8
	s_add_i32 s24, s0, 0xfffe3800
	s_lshl_b32 s25, s93, 11
	s_add_i32 s26, s96, 0xfffffe34
	s_mov_b32 s27, 0
	v_mov_b32_e32 v139, 0
	s_mov_b64 s[6:7], 0x80
	s_mov_b64 s[8:9], 0x40080
	s_mov_b64 s[10:11], 0x100
	s_mov_b64 s[12:13], 0x40100
	s_mov_b64 s[14:15], 0x180
	s_mov_b64 s[16:17], 0x40180
	s_movk_i32 s28, 0x3fff
	s_movk_i32 s29, 0x7c
	s_movk_i32 s30, 0x300
	s_movk_i32 s31, 0x7d
	s_movk_i32 s34, 0x7e
	s_movk_i32 s35, 0x7e1
	s_movk_i32 s36, 0x7f
	v_mov_b32_e32 v137, 1
	v_mov_b32_e32 v156, 0x80
	s_mov_b32 s37, s96
	s_barrier
	s_branch .LBB0_202

.LBB0_469:
	s_or_b64 exec, exec, s[6:7]
	s_mov_b64 s[6:7], exec
	v_mbcnt_lo_u32_b32 v0, s6, 0
	v_mbcnt_hi_u32_b32 v0, s7, v0
	v_cmp_eq_u32_e32 vcc, 0, v0
	s_and_saveexec_b64 s[8:9], vcc
	s_cbranch_execz .LBB0_471
	s_bcnt1_i32_b64 s3, s[6:7]
	v_mov_b32_e32 v0, 0x2000
	v_mov_b32_e32 v1, s3
	global_atomic_add v0, v1, s[4:5] offset:1024
.LBB0_471:
	s_or_b64 exec, exec, s[8:9]
.LBB0_472:
	s_or_b64 exec, exec, s[0:1]
	s_cmpk_gt_u32 s2, 0x7f
	s_waitcnt lgkmcnt(0)
	s_barrier
	s_cbranch_scc1 .LBB0_496
	v_mov_b32_e32 v65, v136
	v_mov_b32_e32 v16, v136
	s_barrier
	s_lshr_b32 s0, s2, 2
	v_bfe_i32 v2, v16, 27, 1
	v_lshlrev_b32_e32 v1, 4, v16
	v_lshrrev_b32_e32 v2, 22, v2
	v_add_u32_e32 v2, v1, v2
	v_and_b32_e32 v2, 0xfffffc00, v2
	v_sub_u32_e32 v2, v1, v2
	s_and_b32 s12, s2, 3
	s_mov_b32 s1, 0
	v_ashrrev_i32_e32 v0, 31, v16
	v_lshrrev_b32_e32 v3, 4, v2
	s_lshl_b64 s[8:9], s[0:1], 10
	s_lshl_b32 s3, s12, 8
	v_lshrrev_b32_e32 v0, 26, v0
	v_bitop3_b32 v2, v3, v2, 32 bitop3:0x6c
	s_or_b32 s4, s8, s3
	v_add_u32_e32 v0, v16, v0
	v_ashrrev_i32_e32 v4, 31, v2
	s_mul_i32 s5, s4, 0x300
	s_mul_hi_u32 s4, s4, 0x300
	s_mul_i32 s6, s9, 0x300
	v_readlane_b32 s16, v254, 4
	v_ashrrev_i32_e32 v0, 6, v0
	v_lshrrev_b32_e32 v4, 26, v4
	s_add_i32 s6, s4, s6
	v_readlane_b32 s28, v254, 16
	v_lshlrev_b32_e32 v3, 3, v0
	v_add_u32_e32 v4, v2, v4
	v_readlane_b32 s29, v254, 17
	s_add_u32 s4, s28, s5
	v_and_b32_e32 v3, -16, v3
	v_ashrrev_i32_e32 v5, 6, v4
	v_and_b32_e32 v4, 0xc0, v4
	v_readlane_b32 s24, v254, 12
	s_addc_u32 s5, s29, s6
	s_lshl_b64 s[6:7], s[0:1], 17
	v_add_u32_e32 v3, v5, v3
	v_lshlrev_b32_e32 v0, 5, v0
	v_sub_u32_e32 v2, v2, v4
	v_mov_b32_e32 v5, 1
	s_add_u32 s10, s24, s6
	v_and_b32_e32 v0, 32, v0
	v_ashrrev_i16_sdwa v2, v5, sext(v2) dst_sel:DWORD dst_unused:UNUSED_PAD src0_sel:DWORD src1_sel:BYTE_0
	s_movk_i32 s6, 0x180
	v_add_u32_sdwa v2, v0, sext(v2) dst_sel:DWORD dst_unused:UNUSED_PAD src0_sel:DWORD src1_sel:WORD_0
	v_mul_lo_u32 v0, v3, s6
	v_lshlrev_b32_e32 v3, 9, v3
	v_add_u32_e32 v1, 0x2000, v1
	v_add_lshl_u32 v0, v2, v0, 1
	v_lshl_add_u32 v4, v2, 1, v3
	v_ashrrev_i32_e32 v2, 31, v1
	v_lshrrev_b32_e32 v2, 22, v2
	v_add_u32_e32 v2, v1, v2
	v_ashrrev_i32_e32 v2, 10, v2
	v_mul_i32_i24_e32 v3, 0x400, v2
	v_sub_u32_e32 v1, v1, v3
	v_lshrrev_b32_e32 v3, 4, v1
	v_bitop3_b32 v1, v3, v1, 32 bitop3:0x6c
	v_ashrrev_i32_e32 v6, 31, v1
	v_lshrrev_b32_e32 v6, 26, v6
	v_readlane_b32 s25, v254, 13
	v_readfirstlane_b32 s13, v16
	v_add_u32_e32 v6, v1, v6
	s_addc_u32 s11, s25, s7
	v_lshlrev_b32_e32 v3, 3, v2
	v_ashrrev_i32_e32 v7, 6, v6
	v_and_b32_e32 v6, 0xc0, v6
	s_ashr_i32 s16, s13, 6
	v_readlane_b32 s22, v254, 10
	v_and_b32_e32 v3, -16, v3
	v_lshlrev_b32_e32 v2, 5, v2
	v_sub_u32_e32 v1, v1, v6
	s_lshl_b32 s25, s16, 10
	v_add_u32_e32 v3, v7, v3
	v_and_b32_e32 v2, 32, v2
	v_ashrrev_i16_sdwa v1, v5, sext(v1) dst_sel:DWORD dst_unused:UNUSED_PAD src0_sel:DWORD src1_sel:BYTE_0
	s_add_i32 s22, s25, 0
	v_add_u32_sdwa v1, v2, sext(v1) dst_sel:DWORD dst_unused:UNUSED_PAD src0_sel:DWORD src1_sel:WORD_0
	v_mul_lo_u32 v2, v3, s6
	v_lshlrev_b32_e32 v3, 9, v3
	s_add_i32 m0, s22, 0x10000
	s_ashr_i32 s14, s13, 8
	v_lshl_add_u32 v6, v1, 1, v3
	global_load_lds_dwordx4 v4, s[10:11]
	s_add_i32 m0, s22, 0x12000
	s_add_i32 s24, s22, 0x2000
	v_readlane_b32 s21, v254, 9
	global_load_lds_dwordx4 v6, s[10:11]
	s_mov_b32 m0, s22
	s_add_u32 s6, s10, 0x10000
	v_readlane_b32 s19, v254, 7
	v_add_lshl_u32 v2, v1, v2, 1
	global_load_lds_dwordx4 v0, s[4:5]
	s_mov_b32 m0, s24
	s_addc_u32 s7, s11, 0
	s_add_i32 s21, s22, 0x14000
	global_load_lds_dwordx4 v2, s[4:5]
	s_mov_b32 m0, s21
	s_add_i32 s19, s22, 0x16000
	global_load_lds_dwordx4 v4, s[6:7]
	s_mov_b32 m0, s19
	v_readlane_b32 s17, v254, 5
	global_load_lds_dwordx4 v6, s[6:7]
	s_add_u32 s6, s4, 0x18000
	s_addc_u32 s7, s5, 0
	s_add_i32 s17, s22, 0x4000
	s_mov_b32 m0, s17
	s_add_i32 s15, s22, 0x6000
	global_load_lds_dwordx4 v0, s[6:7]
	s_mov_b32 m0, s15
	v_mov_b32_e32 v5, 0
	global_load_lds_dwordx4 v2, s[6:7]
	v_mov_b32_e32 v7, v5
	v_mov_b32_e32 v1, v5
	v_mov_b32_e32 v3, v5
	v_lshl_add_u64 v[14:15], s[10:11], 0, v[4:5]
	v_lshl_add_u64 v[12:13], s[10:11], 0, v[6:7]
	v_lshl_add_u64 v[8:9], s[4:5], 0, v[0:1]
	s_cmp_lg_u32 s14, 1
	v_lshl_add_u64 v[10:11], s[4:5], 0, v[2:3]
	v_readlane_b32 s18, v254, 6
	v_readlane_b32 s20, v254, 8
	v_readlane_b32 s23, v254, 11
	v_readlane_b32 s26, v254, 14
	v_readlane_b32 s27, v254, 15
	v_readlane_b32 s30, v254, 18
	v_readlane_b32 s31, v254, 19
	s_cbranch_scc1 .LBB0_475
	s_barrier

.LBB0_605:
	s_or_b64 exec, exec, s[8:9]
.LBB0_606:
	s_or_b64 exec, exec, s[0:1]
	s_cmpk_gt_i32 s96, 0x83
	s_mov_b64 s[0:1], -1
	s_waitcnt lgkmcnt(0)
	s_barrier
	s_cbranch_scc0 .LBB0_705
	s_cmpk_gt_u32 s96, 0x353
	s_cbranch_scc1 .LBB0_704
	s_add_i32 s3, s96, 0x6c
	s_add_i32 s23, s38, 0xffffff7c
	v_readlane_b32 s4, v253, 3
	v_readlane_b32 s5, v253, 4
	s_add_u32 s0, s4, 0x4000
	v_lshlrev_b32_e32 v0, 2, v136
	s_addc_u32 s1, s5, 0
	v_readlane_b32 s72, v253, 51
	v_lshrrev_b32_e32 v16, 4, v136
	v_and_b32_e32 v0, 60, v0
	v_lshlrev_b32_e32 v2, 3, v136
	v_readlane_b32 s12, v253, 11
	v_readlane_b32 s13, v253, 12
	v_readlane_b32 s14, v253, 13
	v_readlane_b32 s15, v253, 14
	v_readlane_b32 s16, v253, 15
	v_readlane_b32 s17, v253, 16
	v_readlane_b32 s18, v253, 17
	v_readlane_b32 s19, v253, 18
	s_add_u32 s4, s4, 0x2000
	v_readlane_b32 s80, v253, 59
	v_readlane_b32 s81, v253, 60
	v_lshl_add_u32 v1, v0, 2, 0
	v_mul_u32_u24_e32 v3, 0x104, v16
	v_lshrrev_b32_e32 v25, 3, v136
	v_and_b32_e32 v2, 56, v2
	v_readlane_b32 s6, v253, 5
	s_addc_u32 s5, s5, 0
	v_readlane_b32 s82, v253, 61
	v_readlane_b32 s83, v253, 62
	v_readlane_b32 s84, v253, 63
	v_readlane_b32 s85, v254, 0
	v_readlane_b32 s86, v254, 1
	v_readlane_b32 s87, v254, 2
	s_mov_b64 s[12:13], s[80:81]
	v_mov_b32_e32 v19, 0
	v_mul_u32_u24_e32 v4, 0x104, v2
	v_lshlrev_b32_e32 v5, 2, v25
	v_readlane_b32 s7, v253, 6
	s_add_u32 s6, s12, 0x200000
	v_add_u32_e32 v31, v1, v3
	v_add_u32_e32 v23, 32, v16
	s_movk_i32 s22, 0x80
	v_or_b32_e32 v28, 0x80, v25
	v_or_b32_e32 v29, 0xfffffc80, v25
	v_add3_u32 v30, 0, v4, v5
	s_addc_u32 s7, s13, 0
	v_mov_b32_e32 v17, v19
	s_add_i32 s24, s96, 0xfffffd5c
	v_lshlrev_b32_e32 v20, 2, v0
	v_mov_b32_e32 v21, v19
	v_add_u32_e32 v32, 0x2080, v31
	v_add_u32_e32 v33, 0x2088, v31
	v_add_u32_e32 v34, 0x4100, v31
	v_add_u32_e32 v35, 0x4108, v31
	v_add_u32_e32 v36, 0x6180, v31
	v_add_u32_e32 v37, 0x6188, v31
	v_add_u32_e32 v38, 0x8200, v31
	v_add_u32_e32 v39, 0x8208, v31
	v_add_u32_e32 v40, 0xa280, v31
	v_add_u32_e32 v41, 0xa288, v31
	s_movk_i32 s25, 0x1ff
	v_lshlrev_b32_e32 v18, 1, v2
	s_movk_i32 s26, 0xff00
	v_add_u32_e32 v42, 0xc300, v31
	v_add_u32_e32 v43, 0xc308, v31
	v_add_u32_e32 v44, 0xe380, v31
	v_add_u32_e32 v45, 0xe388, v31
	v_readlane_b32 s8, v253, 7
	v_readlane_b32 s9, v253, 8
	v_readlane_b32 s10, v253, 9
	v_readlane_b32 s11, v253, 10
	v_readlane_b32 s73, v253, 52
	v_readlane_b32 s74, v253, 53
	v_readlane_b32 s75, v253, 54
	v_readlane_b32 s76, v253, 55
	v_readlane_b32 s77, v253, 56
	v_readlane_b32 s78, v253, 57
	v_readlane_b32 s79, v253, 58
	s_mov_b64 s[14:15], s[82:83]
	s_mov_b64 s[16:17], s[84:85]
	s_mov_b64 s[18:19], s[86:87]
	s_branch .LBB0_612

.LBB0_767:
	s_or_b64 exec, exec, s[8:9]
.LBB0_768:
	s_or_b64 exec, exec, s[0:1]
	s_cmpk_lt_i32 s2, 0x100
	v_bfe_u32 v183, v136, 1, 2
	s_movk_i32 s0, 0x100
	s_cselect_b64 s[10:11], -1, 0
	s_cmpk_gt_i32 s2, 0xff
	v_lshrrev_b32_e32 v187, 6, v136
	v_lshlrev_b32_e32 v190, 11, v136
	v_lshrrev_b32_e32 v252, 1, v136
	v_and_b32_e32 v132, 48, v136
	v_and_b32_e32 v189, 63, v136
	v_lshrrev_b32_e32 v182, 3, v136
	v_lshlrev_b32_e32 v188, 2, v136
	v_lshl_add_u32 v186, v183, 6, 0
	s_waitcnt lgkmcnt(0)
	s_barrier
	s_cbranch_scc1 .LBB0_774
	v_readlane_b32 s12, v253, 51
	v_and_b32_e32 v0, 0x7800, v190
	v_mov_b32_e32 v1, 0
	v_readlane_b32 s24, v253, 63
	v_readlane_b32 s25, v254, 0
	v_mov_b32_e32 v133, v1
	v_and_b32_e32 v7, 4, v188
	v_lshl_add_u64 v[2:3], s[24:25], 0, v[0:1]
	v_lshl_add_u64 v[4:5], v[2:3], 0, v[132:133]
	v_lshl_add_u64 v[2:3], s[56:57], 0, v[0:1]
	v_and_or_b32 v6, v182, 16, v7
	v_lshl_add_u64 v[2:3], v[2:3], 0, v[132:133]
	v_lshlrev_b32_e32 v0, 8, v187
	v_and_b32_e32 v9, 60, v252
	v_lshlrev_b32_e32 v6, 8, v6
	v_readlane_b32 s14, v253, 53
	v_readlane_b32 s15, v253, 54
	v_readlane_b32 s16, v253, 55
	v_readlane_b32 s17, v253, 56
	v_readlane_b32 s18, v253, 57
	v_lshl_add_u64 v[2:3], v[2:3], 0, v[0:1]
	v_lshl_add_u64 v[4:5], v[4:5], 0, v[0:1]
	v_lshlrev_b32_e32 v0, 13, v187
	v_lshl_add_u32 v8, v189, 2, 0
	v_add3_u32 v6, v186, v9, v6
	v_and_b32_e32 v9, 7, v136
	s_mov_b32 s7, 0
	v_cmp_gt_u32_e32 vcc, s0, v136
	v_lshl_or_b32 v7, v183, 3, v7
	v_cmp_eq_u32_e64 s[0:1], 0, v9
	s_lshl_b32 s3, s2, 5
	s_lshl_b32 s14, s38, 5
	s_mov_b32 s15, 0x8000
	s_mov_b32 s16, 0x40000
	s_mov_b32 s17, 0x48000
	v_add_u32_e32 v8, v8, v0
	v_mbcnt_hi_u32_b32 v9, -1, v137
	s_mov_b32 s18, s2
	v_readlane_b32 s13, v253, 52
	v_readlane_b32 s19, v253, 58
	v_readlane_b32 s20, v253, 59
	v_readlane_b32 s21, v253, 60
	v_readlane_b32 s22, v253, 61
	v_readlane_b32 s23, v253, 62
	v_readlane_b32 s26, v254, 1
	v_readlane_b32 s27, v254, 2
	s_branch .LBB0_771

.LBB0_849:
	s_or_b64 exec, exec, s[6:7]
	s_mov_b64 s[6:7], exec
	v_mbcnt_lo_u32_b32 v140, s6, 0
	v_mbcnt_hi_u32_b32 v140, s7, v140
	v_cmp_eq_u32_e32 vcc, 0, v140
	s_and_saveexec_b64 s[8:9], vcc
	s_cbranch_execz .LBB0_851
	s_bcnt1_i32_b64 s3, s[6:7]
	v_mov_b32_e32 v140, 0x2000
	v_mov_b32_e32 v141, s3
	global_atomic_add v140, v141, s[4:5] offset:1024
.LBB0_851:
	s_or_b64 exec, exec, s[8:9]
.LBB0_852:
	s_or_b64 exec, exec, s[0:1]
	s_waitcnt lgkmcnt(0)
	s_barrier
	s_and_b32 s98, s2, 7
	s_lshl_b32 s98, s98, 3
	s_bfe_u32 s99, s2, 0x30003
	s_or_b32 s98, s98, s99
	s_lshr_b32 s99, s2, 6
	v_and_b32_e32 v172, 0xff, v136
	v_lshrrev_b32_e32 v173, 8, v136
	v_mul_u32_u24_e32 v173, 0x84000, v173
	v_lshl_add_u32 v172, v172, 2, v173
	s_lshl_b32 s24, s98, 10
	s_add_u32 s18, s44, s24
	s_addc_u32 s19, s45, 0
	global_load_dword v164, v172, s[18:19]
	s_add_u32 s18, s18, 0x10800
	s_addc_u32 s19, s19, 0
	global_load_dword v165, v172, s[18:19]
	s_add_u32 s18, s18, 0x10800
	s_addc_u32 s19, s19, 0
	global_load_dword v166, v172, s[18:19]
	s_add_u32 s18, s18, 0x10800
	s_addc_u32 s19, s19, 0
	global_load_dword v167, v172, s[18:19]
	s_add_u32 s18, s18, 0x10800
	s_addc_u32 s19, s19, 0
	global_load_dword v168, v172, s[18:19]
	s_add_u32 s18, s18, 0x10800
	s_addc_u32 s19, s19, 0
	global_load_dword v169, v172, s[18:19]
	s_add_u32 s18, s18, 0x10800
	s_addc_u32 s19, s19, 0
	global_load_dword v170, v172, s[18:19]
	s_add_u32 s18, s18, 0x10800
	s_addc_u32 s19, s19, 0
	global_load_dword v171, v172, s[18:19]
	v_lshrrev_b32_e32 v141, 8, v136
	v_and_b32_e32 v142, 15, v136
	v_lshl_add_u32 v141, v141, 6, v142
	v_bfe_u32 v144, v136, 6, 2
	v_bfe_u32 v145, v136, 4, 2
	v_lshlrev_b32_e32 v144, 5, v144
	v_lshl_add_u32 v144, v145, 3, v144
	s_lshl_b32 s24, s99, 8
	v_add_u32_e32 v144, s24, v144
	s_lshl_b32 s25, s98, 8
	v_add_u32_e32 v145, s25, v141
	v_lshl_add_u32 v146, v145, 10, v144
	v_lshlrev_b32_e32 v140, 1, v146
	v_lshlrev_b32_e32 v147, 2, v144
	v_readlane_b32 s18, v253, 3
	v_readlane_b32 s19, v253, 4
	v_readlane_b32 s20, v253, 53
	v_readlane_b32 s21, v253, 54
	s_nop 4
	s_add_u32 s18, s18, 0x1000
	s_addc_u32 s19, s19, 0
	global_load_dwordx4 v[148:151], v147, s[18:19]
	global_load_dwordx4 v[152:155], v147, s[18:19] offset:16
	global_load_dwordx4 v[156:159], v147, s[18:19] offset:512
	global_load_dwordx4 v[160:163], v147, s[18:19] offset:528
	s_add_u32 s22, s20, 0x0
	s_addc_u32 s23, s21, 0
	global_load_dwordx4 v[188:191], v140, s[22:23] nt
	global_load_dwordx4 v[192:195], v140, s[22:23] offset:256 nt
	s_add_u32 s22, s20, 0x8000
	s_addc_u32 s23, s21, 0
	global_load_dwordx4 v[196:199], v140, s[22:23] nt
	global_load_dwordx4 v[200:203], v140, s[22:23] offset:256 nt
	s_add_u32 s22, s20, 0x10000
	s_addc_u32 s23, s21, 0
	global_load_dwordx4 v[204:207], v140, s[22:23] nt
	global_load_dwordx4 v[208:211], v140, s[22:23] offset:256 nt
	s_add_u32 s22, s20, 0x18000
	s_addc_u32 s23, s21, 0
	global_load_dwordx4 v[212:215], v140, s[22:23] nt
	global_load_dwordx4 v[216:219], v140, s[22:23] offset:256 nt
	s_add_u32 s22, s20, 0x40000
	s_addc_u32 s23, s21, 0
	global_load_dwordx4 v[220:223], v140, s[22:23] nt
	global_load_dwordx4 v[224:227], v140, s[22:23] offset:256 nt
	s_add_u32 s22, s20, 0x48000
	s_addc_u32 s23, s21, 0
	global_load_dwordx4 v[228:231], v140, s[22:23] nt
	global_load_dwordx4 v[232:235], v140, s[22:23] offset:256 nt
	s_add_u32 s22, s20, 0x50000
	s_addc_u32 s23, s21, 0
	global_load_dwordx4 v[236:239], v140, s[22:23] nt
	global_load_dwordx4 v[240:243], v140, s[22:23] offset:256 nt
	s_add_u32 s22, s20, 0x58000
	s_addc_u32 s23, s21, 0
	global_load_dwordx4 v[244:247], v140, s[22:23] nt
	global_load_dwordx4 v[248:251], v140, s[22:23] offset:256 nt
	s_waitcnt vmcnt(20)
	v_add_f32_e32 v164, v164, v165
	v_add_f32_e32 v164, v164, v166
	v_add_f32_e32 v164, v164, v167
	v_add_f32_e32 v164, v164, v168
	v_add_f32_e32 v164, v164, v169
	v_add_f32_e32 v164, v164, v170
	v_add_f32_e32 v164, v164, v171
	v_lshlrev_b32_e32 v173, 2, v136
	ds_write_b32 v173, v164
	s_waitcnt lgkmcnt(0)
	s_barrier
	v_lshlrev_b32_e32 v142, 2, v141
	ds_read_b32 v128, v142 offset:0
	ds_read_b32 v174, v142 offset:1024
	ds_read_b32 v129, v142 offset:64
	ds_read_b32 v175, v142 offset:1088
	ds_read_b32 v130, v142 offset:128
	ds_read_b32 v176, v142 offset:1152
	ds_read_b32 v131, v142 offset:192
	ds_read_b32 v177, v142 offset:1216
	ds_read_b32 v132, v142 offset:512
	ds_read_b32 v178, v142 offset:1536
	ds_read_b32 v133, v142 offset:576
	ds_read_b32 v179, v142 offset:1600
	ds_read_b32 v134, v142 offset:640
	ds_read_b32 v180, v142 offset:1664
	ds_read_b32 v135, v142 offset:704
	ds_read_b32 v181, v142 offset:1728
	s_waitcnt lgkmcnt(0)
	s_mov_b32 s101, 0x3a800000
	v_mov_b32_e32 v143, 0x358637bd
	v_add_f32_e32 v128, v128, v174
	v_add_f32_e32 v129, v129, v175
	v_add_f32_e32 v130, v130, v176
	v_add_f32_e32 v131, v131, v177
	v_add_f32_e32 v132, v132, v178
	v_add_f32_e32 v133, v133, v179
	v_add_f32_e32 v134, v134, v180
	v_add_f32_e32 v135, v135, v181
	v_fma_f32 v128, v128, s101, v143
	v_fma_f32 v129, v129, s101, v143
	v_fma_f32 v130, v130, s101, v143
	v_fma_f32 v131, v131, s101, v143
	v_fma_f32 v132, v132, s101, v143
	v_fma_f32 v133, v133, s101, v143
	v_fma_f32 v134, v134, s101, v143
	v_fma_f32 v135, v135, s101, v143
	v_rsq_f32_e32 v128, v128
	v_rsq_f32_e32 v129, v129
	v_rsq_f32_e32 v130, v130
	v_rsq_f32_e32 v131, v131
	v_rsq_f32_e32 v132, v132
	v_rsq_f32_e32 v133, v133
	v_rsq_f32_e32 v134, v134
	v_rsq_f32_e32 v135, v135
	s_waitcnt vmcnt(0)
	s_add_u32 s22, s60, 0x0
	s_addc_u32 s23, s61, 0
	v_lshlrev_b32_e32 v164, 16, v188
	v_and_b32_e32 v165, 0xffff0000, v188
	v_lshlrev_b32_e32 v166, 16, v189
	v_and_b32_e32 v167, 0xffff0000, v189
	v_lshlrev_b32_e32 v168, 16, v190
	v_and_b32_e32 v169, 0xffff0000, v190
	v_lshlrev_b32_e32 v170, 16, v191
	v_and_b32_e32 v171, 0xffff0000, v191
	v_mul_f32_e32 v124, v124, v128
	v_mul_f32_e32 v125, v125, v128
	v_mul_f32_e32 v126, v126, v128
	v_mul_f32_e32 v127, v127, v128
	v_mul_f32_e32 v112, v112, v128
	v_mul_f32_e32 v113, v113, v128
	v_mul_f32_e32 v114, v114, v128
	v_mul_f32_e32 v115, v115, v128
	v_fmac_f32_e32 v164, v124, v148
	v_fmac_f32_e32 v165, v125, v149
	v_fmac_f32_e32 v166, v126, v150
	v_fmac_f32_e32 v167, v127, v151
	v_fmac_f32_e32 v168, v112, v152
	v_fmac_f32_e32 v169, v113, v153
	v_fmac_f32_e32 v170, v114, v154
	v_fmac_f32_e32 v171, v115, v155
	v_mul_f32_e32 v138, v164, v164
	v_fmac_f32_e32 v138, v165, v165
	v_fmac_f32_e32 v138, v166, v166
	v_fmac_f32_e32 v138, v167, v167
	v_fmac_f32_e32 v138, v168, v168
	v_fmac_f32_e32 v138, v169, v169
	v_fmac_f32_e32 v138, v170, v170
	v_fmac_f32_e32 v138, v171, v171
	v_cvt_pk_bf16_f32 v180, v164, v165
	v_cvt_pk_bf16_f32 v181, v166, v167
	v_cvt_pk_bf16_f32 v182, v168, v169
	v_cvt_pk_bf16_f32 v183, v170, v171
	global_store_dwordx4 v140, v[180:183], s[22:23]
	v_lshlrev_b32_e32 v172, 16, v192
	v_and_b32_e32 v173, 0xffff0000, v192
	v_lshlrev_b32_e32 v174, 16, v193
	v_and_b32_e32 v175, 0xffff0000, v193
	v_lshlrev_b32_e32 v176, 16, v194
	v_and_b32_e32 v177, 0xffff0000, v194
	v_lshlrev_b32_e32 v178, 16, v195
	v_and_b32_e32 v179, 0xffff0000, v195
	v_mul_f32_e32 v120, v120, v128
	v_mul_f32_e32 v121, v121, v128
	v_mul_f32_e32 v122, v122, v128
	v_mul_f32_e32 v123, v123, v128
	v_mul_f32_e32 v116, v116, v128
	v_mul_f32_e32 v117, v117, v128
	v_mul_f32_e32 v118, v118, v128
	v_mul_f32_e32 v119, v119, v128
	v_fmac_f32_e32 v172, v120, v156
	v_fmac_f32_e32 v173, v121, v157
	v_fmac_f32_e32 v174, v122, v158
	v_fmac_f32_e32 v175, v123, v159
	v_fmac_f32_e32 v176, v116, v160
	v_fmac_f32_e32 v177, v117, v161
	v_fmac_f32_e32 v178, v118, v162
	v_fmac_f32_e32 v179, v119, v163
	v_fmac_f32_e32 v138, v172, v172
	v_fmac_f32_e32 v138, v173, v173
	v_fmac_f32_e32 v138, v174, v174
	v_fmac_f32_e32 v138, v175, v175
	v_fmac_f32_e32 v138, v176, v176
	v_fmac_f32_e32 v138, v177, v177
	v_fmac_f32_e32 v138, v178, v178
	v_fmac_f32_e32 v138, v179, v179
	v_cvt_pk_bf16_f32 v184, v172, v173
	v_cvt_pk_bf16_f32 v185, v174, v175
	v_cvt_pk_bf16_f32 v186, v176, v177
	v_cvt_pk_bf16_f32 v187, v178, v179
	global_store_dwordx4 v140, v[184:187], s[22:23] offset:256
	s_add_u32 s22, s60, 0x8000
	s_addc_u32 s23, s61, 0
	v_lshlrev_b32_e32 v164, 16, v196
	v_and_b32_e32 v165, 0xffff0000, v196
	v_lshlrev_b32_e32 v166, 16, v197
	v_and_b32_e32 v167, 0xffff0000, v197
	v_lshlrev_b32_e32 v168, 16, v198
	v_and_b32_e32 v169, 0xffff0000, v198
	v_lshlrev_b32_e32 v170, 16, v199
	v_and_b32_e32 v171, 0xffff0000, v199
	v_mul_f32_e32 v108, v108, v129
	v_mul_f32_e32 v109, v109, v129
	v_mul_f32_e32 v110, v110, v129
	v_mul_f32_e32 v111, v111, v129
	v_mul_f32_e32 v96, v96, v129
	v_mul_f32_e32 v97, v97, v129
	v_mul_f32_e32 v98, v98, v129
	v_mul_f32_e32 v99, v99, v129
	v_fmac_f32_e32 v164, v108, v148
	v_fmac_f32_e32 v165, v109, v149
	v_fmac_f32_e32 v166, v110, v150
	v_fmac_f32_e32 v167, v111, v151
	v_fmac_f32_e32 v168, v96, v152
	v_fmac_f32_e32 v169, v97, v153
	v_fmac_f32_e32 v170, v98, v154
	v_fmac_f32_e32 v171, v99, v155
	v_mul_f32_e32 v139, v164, v164
	v_fmac_f32_e32 v139, v165, v165
	v_fmac_f32_e32 v139, v166, v166
	v_fmac_f32_e32 v139, v167, v167
	v_fmac_f32_e32 v139, v168, v168
	v_fmac_f32_e32 v139, v169, v169
	v_fmac_f32_e32 v139, v170, v170
	v_fmac_f32_e32 v139, v171, v171
	v_cvt_pk_bf16_f32 v180, v164, v165
	v_cvt_pk_bf16_f32 v181, v166, v167
	v_cvt_pk_bf16_f32 v182, v168, v169
	v_cvt_pk_bf16_f32 v183, v170, v171
	global_store_dwordx4 v140, v[180:183], s[22:23]
	v_lshlrev_b32_e32 v172, 16, v200
	v_and_b32_e32 v173, 0xffff0000, v200
	v_lshlrev_b32_e32 v174, 16, v201
	v_and_b32_e32 v175, 0xffff0000, v201
	v_lshlrev_b32_e32 v176, 16, v202
	v_and_b32_e32 v177, 0xffff0000, v202
	v_lshlrev_b32_e32 v178, 16, v203
	v_and_b32_e32 v179, 0xffff0000, v203
	v_mul_f32_e32 v100, v100, v129
	v_mul_f32_e32 v101, v101, v129
	v_mul_f32_e32 v102, v102, v129
	v_mul_f32_e32 v103, v103, v129
	v_mul_f32_e32 v104, v104, v129
	v_mul_f32_e32 v105, v105, v129
	v_mul_f32_e32 v106, v106, v129
	v_mul_f32_e32 v107, v107, v129
	v_fmac_f32_e32 v172, v100, v156
	v_fmac_f32_e32 v173, v101, v157
	v_fmac_f32_e32 v174, v102, v158
	v_fmac_f32_e32 v175, v103, v159
	v_fmac_f32_e32 v176, v104, v160
	v_fmac_f32_e32 v177, v105, v161
	v_fmac_f32_e32 v178, v106, v162
	v_fmac_f32_e32 v179, v107, v163
	v_fmac_f32_e32 v139, v172, v172
	v_fmac_f32_e32 v139, v173, v173
	v_fmac_f32_e32 v139, v174, v174
	v_fmac_f32_e32 v139, v175, v175
	v_fmac_f32_e32 v139, v176, v176
	v_fmac_f32_e32 v139, v177, v177
	v_fmac_f32_e32 v139, v178, v178
	v_fmac_f32_e32 v139, v179, v179
	v_cvt_pk_bf16_f32 v184, v172, v173
	v_cvt_pk_bf16_f32 v185, v174, v175
	v_cvt_pk_bf16_f32 v186, v176, v177
	v_cvt_pk_bf16_f32 v187, v178, v179
	global_store_dwordx4 v140, v[184:187], s[22:23] offset:256
	s_add_u32 s22, s60, 0x10000
	s_addc_u32 s23, s61, 0
	v_lshlrev_b32_e32 v164, 16, v204
	v_and_b32_e32 v165, 0xffff0000, v204
	v_lshlrev_b32_e32 v166, 16, v205
	v_and_b32_e32 v167, 0xffff0000, v205
	v_lshlrev_b32_e32 v168, 16, v206
	v_and_b32_e32 v169, 0xffff0000, v206
	v_lshlrev_b32_e32 v170, 16, v207
	v_and_b32_e32 v171, 0xffff0000, v207
	v_mul_f32_e32 v92, v92, v130
	v_mul_f32_e32 v93, v93, v130
	v_mul_f32_e32 v94, v94, v130
	v_mul_f32_e32 v95, v95, v130
	v_mul_f32_e32 v80, v80, v130
	v_mul_f32_e32 v81, v81, v130
	v_mul_f32_e32 v82, v82, v130
	v_mul_f32_e32 v83, v83, v130
	v_fmac_f32_e32 v164, v92, v148
	v_fmac_f32_e32 v165, v93, v149
	v_fmac_f32_e32 v166, v94, v150
	v_fmac_f32_e32 v167, v95, v151
	v_fmac_f32_e32 v168, v80, v152
	v_fmac_f32_e32 v169, v81, v153
	v_fmac_f32_e32 v170, v82, v154
	v_fmac_f32_e32 v171, v83, v155
	v_mul_f32_e32 v141, v164, v164
	v_fmac_f32_e32 v141, v165, v165
	v_fmac_f32_e32 v141, v166, v166
	v_fmac_f32_e32 v141, v167, v167
	v_fmac_f32_e32 v141, v168, v168
	v_fmac_f32_e32 v141, v169, v169
	v_fmac_f32_e32 v141, v170, v170
	v_fmac_f32_e32 v141, v171, v171
	v_cvt_pk_bf16_f32 v180, v164, v165
	v_cvt_pk_bf16_f32 v181, v166, v167
	v_cvt_pk_bf16_f32 v182, v168, v169
	v_cvt_pk_bf16_f32 v183, v170, v171
	global_store_dwordx4 v140, v[180:183], s[22:23]
	v_lshlrev_b32_e32 v172, 16, v208
	v_and_b32_e32 v173, 0xffff0000, v208
	v_lshlrev_b32_e32 v174, 16, v209
	v_and_b32_e32 v175, 0xffff0000, v209
	v_lshlrev_b32_e32 v176, 16, v210
	v_and_b32_e32 v177, 0xffff0000, v210
	v_lshlrev_b32_e32 v178, 16, v211
	v_and_b32_e32 v179, 0xffff0000, v211
	v_mul_f32_e32 v84, v84, v130
	v_mul_f32_e32 v85, v85, v130
	v_mul_f32_e32 v86, v86, v130
	v_mul_f32_e32 v87, v87, v130
	v_mul_f32_e32 v88, v88, v130
	v_mul_f32_e32 v89, v89, v130
	v_mul_f32_e32 v90, v90, v130
	v_mul_f32_e32 v91, v91, v130
	v_fmac_f32_e32 v172, v84, v156
	v_fmac_f32_e32 v173, v85, v157
	v_fmac_f32_e32 v174, v86, v158
	v_fmac_f32_e32 v175, v87, v159
	v_fmac_f32_e32 v176, v88, v160
	v_fmac_f32_e32 v177, v89, v161
	v_fmac_f32_e32 v178, v90, v162
	v_fmac_f32_e32 v179, v91, v163
	v_fmac_f32_e32 v141, v172, v172
	v_fmac_f32_e32 v141, v173, v173
	v_fmac_f32_e32 v141, v174, v174
	v_fmac_f32_e32 v141, v175, v175
	v_fmac_f32_e32 v141, v176, v176
	v_fmac_f32_e32 v141, v177, v177
	v_fmac_f32_e32 v141, v178, v178
	v_fmac_f32_e32 v141, v179, v179
	v_cvt_pk_bf16_f32 v184, v172, v173
	v_cvt_pk_bf16_f32 v185, v174, v175
	v_cvt_pk_bf16_f32 v186, v176, v177
	v_cvt_pk_bf16_f32 v187, v178, v179
	global_store_dwordx4 v140, v[184:187], s[22:23] offset:256
	s_add_u32 s22, s60, 0x18000
	s_addc_u32 s23, s61, 0
	v_lshlrev_b32_e32 v164, 16, v212
	v_and_b32_e32 v165, 0xffff0000, v212
	v_lshlrev_b32_e32 v166, 16, v213
	v_and_b32_e32 v167, 0xffff0000, v213
	v_lshlrev_b32_e32 v168, 16, v214
	v_and_b32_e32 v169, 0xffff0000, v214
	v_lshlrev_b32_e32 v170, 16, v215
	v_and_b32_e32 v171, 0xffff0000, v215
	v_mul_f32_e32 v76, v76, v131
	v_mul_f32_e32 v77, v77, v131
	v_mul_f32_e32 v78, v78, v131
	v_mul_f32_e32 v79, v79, v131
	v_mul_f32_e32 v64, v64, v131
	v_mul_f32_e32 v65, v65, v131
	v_mul_f32_e32 v66, v66, v131
	v_mul_f32_e32 v67, v67, v131
	v_fmac_f32_e32 v164, v76, v148
	v_fmac_f32_e32 v165, v77, v149
	v_fmac_f32_e32 v166, v78, v150
	v_fmac_f32_e32 v167, v79, v151
	v_fmac_f32_e32 v168, v64, v152
	v_fmac_f32_e32 v169, v65, v153
	v_fmac_f32_e32 v170, v66, v154
	v_fmac_f32_e32 v171, v67, v155
	v_mul_f32_e32 v142, v164, v164
	v_fmac_f32_e32 v142, v165, v165
	v_fmac_f32_e32 v142, v166, v166
	v_fmac_f32_e32 v142, v167, v167
	v_fmac_f32_e32 v142, v168, v168
	v_fmac_f32_e32 v142, v169, v169
	v_fmac_f32_e32 v142, v170, v170
	v_fmac_f32_e32 v142, v171, v171
	v_cvt_pk_bf16_f32 v180, v164, v165
	v_cvt_pk_bf16_f32 v181, v166, v167
	v_cvt_pk_bf16_f32 v182, v168, v169
	v_cvt_pk_bf16_f32 v183, v170, v171
	global_store_dwordx4 v140, v[180:183], s[22:23]
	v_lshlrev_b32_e32 v172, 16, v216
	v_and_b32_e32 v173, 0xffff0000, v216
	v_lshlrev_b32_e32 v174, 16, v217
	v_and_b32_e32 v175, 0xffff0000, v217
	v_lshlrev_b32_e32 v176, 16, v218
	v_and_b32_e32 v177, 0xffff0000, v218
	v_lshlrev_b32_e32 v178, 16, v219
	v_and_b32_e32 v179, 0xffff0000, v219
	v_mul_f32_e32 v68, v68, v131
	v_mul_f32_e32 v69, v69, v131
	v_mul_f32_e32 v70, v70, v131
	v_mul_f32_e32 v71, v71, v131
	v_mul_f32_e32 v72, v72, v131
	v_mul_f32_e32 v73, v73, v131
	v_mul_f32_e32 v74, v74, v131
	v_mul_f32_e32 v75, v75, v131
	v_fmac_f32_e32 v172, v68, v156
	v_fmac_f32_e32 v173, v69, v157
	v_fmac_f32_e32 v174, v70, v158
	v_fmac_f32_e32 v175, v71, v159
	v_fmac_f32_e32 v176, v72, v160
	v_fmac_f32_e32 v177, v73, v161
	v_fmac_f32_e32 v178, v74, v162
	v_fmac_f32_e32 v179, v75, v163
	v_fmac_f32_e32 v142, v172, v172
	v_fmac_f32_e32 v142, v173, v173
	v_fmac_f32_e32 v142, v174, v174
	v_fmac_f32_e32 v142, v175, v175
	v_fmac_f32_e32 v142, v176, v176
	v_fmac_f32_e32 v142, v177, v177
	v_fmac_f32_e32 v142, v178, v178
	v_fmac_f32_e32 v142, v179, v179
	v_cvt_pk_bf16_f32 v184, v172, v173
	v_cvt_pk_bf16_f32 v185, v174, v175
	v_cvt_pk_bf16_f32 v186, v176, v177
	v_cvt_pk_bf16_f32 v187, v178, v179
	global_store_dwordx4 v140, v[184:187], s[22:23] offset:256
	s_add_u32 s22, s60, 0x40000
	s_addc_u32 s23, s61, 0
	v_lshlrev_b32_e32 v164, 16, v220
	v_and_b32_e32 v165, 0xffff0000, v220
	v_lshlrev_b32_e32 v166, 16, v221
	v_and_b32_e32 v167, 0xffff0000, v221
	v_lshlrev_b32_e32 v168, 16, v222
	v_and_b32_e32 v169, 0xffff0000, v222
	v_lshlrev_b32_e32 v170, 16, v223
	v_and_b32_e32 v171, 0xffff0000, v223
	v_mul_f32_e32 v60, v60, v132
	v_mul_f32_e32 v61, v61, v132
	v_mul_f32_e32 v62, v62, v132
	v_mul_f32_e32 v63, v63, v132
	v_mul_f32_e32 v48, v48, v132
	v_mul_f32_e32 v49, v49, v132
	v_mul_f32_e32 v50, v50, v132
	v_mul_f32_e32 v51, v51, v132
	v_fmac_f32_e32 v164, v60, v148
	v_fmac_f32_e32 v165, v61, v149
	v_fmac_f32_e32 v166, v62, v150
	v_fmac_f32_e32 v167, v63, v151
	v_fmac_f32_e32 v168, v48, v152
	v_fmac_f32_e32 v169, v49, v153
	v_fmac_f32_e32 v170, v50, v154
	v_fmac_f32_e32 v171, v51, v155
	v_mul_f32_e32 v143, v164, v164
	v_fmac_f32_e32 v143, v165, v165
	v_fmac_f32_e32 v143, v166, v166
	v_fmac_f32_e32 v143, v167, v167
	v_fmac_f32_e32 v143, v168, v168
	v_fmac_f32_e32 v143, v169, v169
	v_fmac_f32_e32 v143, v170, v170
	v_fmac_f32_e32 v143, v171, v171
	v_cvt_pk_bf16_f32 v180, v164, v165
	v_cvt_pk_bf16_f32 v181, v166, v167
	v_cvt_pk_bf16_f32 v182, v168, v169
	v_cvt_pk_bf16_f32 v183, v170, v171
	global_store_dwordx4 v140, v[180:183], s[22:23]
	v_lshlrev_b32_e32 v172, 16, v224
	v_and_b32_e32 v173, 0xffff0000, v224
	v_lshlrev_b32_e32 v174, 16, v225
	v_and_b32_e32 v175, 0xffff0000, v225
	v_lshlrev_b32_e32 v176, 16, v226
	v_and_b32_e32 v177, 0xffff0000, v226
	v_lshlrev_b32_e32 v178, 16, v227
	v_and_b32_e32 v179, 0xffff0000, v227
	v_mul_f32_e32 v52, v52, v132
	v_mul_f32_e32 v53, v53, v132
	v_mul_f32_e32 v54, v54, v132
	v_mul_f32_e32 v55, v55, v132
	v_mul_f32_e32 v56, v56, v132
	v_mul_f32_e32 v57, v57, v132
	v_mul_f32_e32 v58, v58, v132
	v_mul_f32_e32 v59, v59, v132
	v_fmac_f32_e32 v172, v52, v156
	v_fmac_f32_e32 v173, v53, v157
	v_fmac_f32_e32 v174, v54, v158
	v_fmac_f32_e32 v175, v55, v159
	v_fmac_f32_e32 v176, v56, v160
	v_fmac_f32_e32 v177, v57, v161
	v_fmac_f32_e32 v178, v58, v162
	v_fmac_f32_e32 v179, v59, v163
	v_fmac_f32_e32 v143, v172, v172
	v_fmac_f32_e32 v143, v173, v173
	v_fmac_f32_e32 v143, v174, v174
	v_fmac_f32_e32 v143, v175, v175
	v_fmac_f32_e32 v143, v176, v176
	v_fmac_f32_e32 v143, v177, v177
	v_fmac_f32_e32 v143, v178, v178
	v_fmac_f32_e32 v143, v179, v179
	v_cvt_pk_bf16_f32 v184, v172, v173
	v_cvt_pk_bf16_f32 v185, v174, v175
	v_cvt_pk_bf16_f32 v186, v176, v177
	v_cvt_pk_bf16_f32 v187, v178, v179
	global_store_dwordx4 v140, v[184:187], s[22:23] offset:256
	s_add_u32 s22, s60, 0x48000
	s_addc_u32 s23, s61, 0
	v_lshlrev_b32_e32 v164, 16, v228
	v_and_b32_e32 v165, 0xffff0000, v228
	v_lshlrev_b32_e32 v166, 16, v229
	v_and_b32_e32 v167, 0xffff0000, v229
	v_lshlrev_b32_e32 v168, 16, v230
	v_and_b32_e32 v169, 0xffff0000, v230
	v_lshlrev_b32_e32 v170, 16, v231
	v_and_b32_e32 v171, 0xffff0000, v231
	v_mul_f32_e32 v44, v44, v133
	v_mul_f32_e32 v45, v45, v133
	v_mul_f32_e32 v46, v46, v133
	v_mul_f32_e32 v47, v47, v133
	v_mul_f32_e32 v32, v32, v133
	v_mul_f32_e32 v33, v33, v133
	v_mul_f32_e32 v34, v34, v133
	v_mul_f32_e32 v35, v35, v133
	v_fmac_f32_e32 v164, v44, v148
	v_fmac_f32_e32 v165, v45, v149
	v_fmac_f32_e32 v166, v46, v150
	v_fmac_f32_e32 v167, v47, v151
	v_fmac_f32_e32 v168, v32, v152
	v_fmac_f32_e32 v169, v33, v153
	v_fmac_f32_e32 v170, v34, v154
	v_fmac_f32_e32 v171, v35, v155
	v_mul_f32_e32 v144, v164, v164
	v_fmac_f32_e32 v144, v165, v165
	v_fmac_f32_e32 v144, v166, v166
	v_fmac_f32_e32 v144, v167, v167
	v_fmac_f32_e32 v144, v168, v168
	v_fmac_f32_e32 v144, v169, v169
	v_fmac_f32_e32 v144, v170, v170
	v_fmac_f32_e32 v144, v171, v171
	v_cvt_pk_bf16_f32 v180, v164, v165
	v_cvt_pk_bf16_f32 v181, v166, v167
	v_cvt_pk_bf16_f32 v182, v168, v169
	v_cvt_pk_bf16_f32 v183, v170, v171
	global_store_dwordx4 v140, v[180:183], s[22:23]
	v_lshlrev_b32_e32 v172, 16, v232
	v_and_b32_e32 v173, 0xffff0000, v232
	v_lshlrev_b32_e32 v174, 16, v233
	v_and_b32_e32 v175, 0xffff0000, v233
	v_lshlrev_b32_e32 v176, 16, v234
	v_and_b32_e32 v177, 0xffff0000, v234
	v_lshlrev_b32_e32 v178, 16, v235
	v_and_b32_e32 v179, 0xffff0000, v235
	v_mul_f32_e32 v36, v36, v133
	v_mul_f32_e32 v37, v37, v133
	v_mul_f32_e32 v38, v38, v133
	v_mul_f32_e32 v39, v39, v133
	v_mul_f32_e32 v40, v40, v133
	v_mul_f32_e32 v41, v41, v133
	v_mul_f32_e32 v42, v42, v133
	v_mul_f32_e32 v43, v43, v133
	v_fmac_f32_e32 v172, v36, v156
	v_fmac_f32_e32 v173, v37, v157
	v_fmac_f32_e32 v174, v38, v158
	v_fmac_f32_e32 v175, v39, v159
	v_fmac_f32_e32 v176, v40, v160
	v_fmac_f32_e32 v177, v41, v161
	v_fmac_f32_e32 v178, v42, v162
	v_fmac_f32_e32 v179, v43, v163
	v_fmac_f32_e32 v144, v172, v172
	v_fmac_f32_e32 v144, v173, v173
	v_fmac_f32_e32 v144, v174, v174
	v_fmac_f32_e32 v144, v175, v175
	v_fmac_f32_e32 v144, v176, v176
	v_fmac_f32_e32 v144, v177, v177
	v_fmac_f32_e32 v144, v178, v178
	v_fmac_f32_e32 v144, v179, v179
	v_cvt_pk_bf16_f32 v184, v172, v173
	v_cvt_pk_bf16_f32 v185, v174, v175
	v_cvt_pk_bf16_f32 v186, v176, v177
	v_cvt_pk_bf16_f32 v187, v178, v179
	global_store_dwordx4 v140, v[184:187], s[22:23] offset:256
	s_add_u32 s22, s60, 0x50000
	s_addc_u32 s23, s61, 0
	v_lshlrev_b32_e32 v164, 16, v236
	v_and_b32_e32 v165, 0xffff0000, v236
	v_lshlrev_b32_e32 v166, 16, v237
	v_and_b32_e32 v167, 0xffff0000, v237
	v_lshlrev_b32_e32 v168, 16, v238
	v_and_b32_e32 v169, 0xffff0000, v238
	v_lshlrev_b32_e32 v170, 16, v239
	v_and_b32_e32 v171, 0xffff0000, v239
	v_mul_f32_e32 v28, v28, v134
	v_mul_f32_e32 v29, v29, v134
	v_mul_f32_e32 v30, v30, v134
	v_mul_f32_e32 v31, v31, v134
	v_mul_f32_e32 v16, v16, v134
	v_mul_f32_e32 v17, v17, v134
	v_mul_f32_e32 v18, v18, v134
	v_mul_f32_e32 v19, v19, v134
	v_fmac_f32_e32 v164, v28, v148
	v_fmac_f32_e32 v165, v29, v149
	v_fmac_f32_e32 v166, v30, v150
	v_fmac_f32_e32 v167, v31, v151
	v_fmac_f32_e32 v168, v16, v152
	v_fmac_f32_e32 v169, v17, v153
	v_fmac_f32_e32 v170, v18, v154
	v_fmac_f32_e32 v171, v19, v155
	v_mul_f32_e32 v145, v164, v164
	v_fmac_f32_e32 v145, v165, v165
	v_fmac_f32_e32 v145, v166, v166
	v_fmac_f32_e32 v145, v167, v167
	v_fmac_f32_e32 v145, v168, v168
	v_fmac_f32_e32 v145, v169, v169
	v_fmac_f32_e32 v145, v170, v170
	v_fmac_f32_e32 v145, v171, v171
	v_cvt_pk_bf16_f32 v180, v164, v165
	v_cvt_pk_bf16_f32 v181, v166, v167
	v_cvt_pk_bf16_f32 v182, v168, v169
	v_cvt_pk_bf16_f32 v183, v170, v171
	global_store_dwordx4 v140, v[180:183], s[22:23]
	v_lshlrev_b32_e32 v172, 16, v240
	v_and_b32_e32 v173, 0xffff0000, v240
	v_lshlrev_b32_e32 v174, 16, v241
	v_and_b32_e32 v175, 0xffff0000, v241
	v_lshlrev_b32_e32 v176, 16, v242
	v_and_b32_e32 v177, 0xffff0000, v242
	v_lshlrev_b32_e32 v178, 16, v243
	v_and_b32_e32 v179, 0xffff0000, v243
	v_mul_f32_e32 v20, v20, v134
	v_mul_f32_e32 v21, v21, v134
	v_mul_f32_e32 v22, v22, v134
	v_mul_f32_e32 v23, v23, v134
	v_mul_f32_e32 v24, v24, v134
	v_mul_f32_e32 v25, v25, v134
	v_mul_f32_e32 v26, v26, v134
	v_mul_f32_e32 v27, v27, v134
	v_fmac_f32_e32 v172, v20, v156
	v_fmac_f32_e32 v173, v21, v157
	v_fmac_f32_e32 v174, v22, v158
	v_fmac_f32_e32 v175, v23, v159
	v_fmac_f32_e32 v176, v24, v160
	v_fmac_f32_e32 v177, v25, v161
	v_fmac_f32_e32 v178, v26, v162
	v_fmac_f32_e32 v179, v27, v163
	v_fmac_f32_e32 v145, v172, v172
	v_fmac_f32_e32 v145, v173, v173
	v_fmac_f32_e32 v145, v174, v174
	v_fmac_f32_e32 v145, v175, v175
	v_fmac_f32_e32 v145, v176, v176
	v_fmac_f32_e32 v145, v177, v177
	v_fmac_f32_e32 v145, v178, v178
	v_fmac_f32_e32 v145, v179, v179
	v_cvt_pk_bf16_f32 v184, v172, v173
	v_cvt_pk_bf16_f32 v185, v174, v175
	v_cvt_pk_bf16_f32 v186, v176, v177
	v_cvt_pk_bf16_f32 v187, v178, v179
	global_store_dwordx4 v140, v[184:187], s[22:23] offset:256
	s_add_u32 s22, s60, 0x58000
	s_addc_u32 s23, s61, 0
	v_lshlrev_b32_e32 v164, 16, v244
	v_and_b32_e32 v165, 0xffff0000, v244
	v_lshlrev_b32_e32 v166, 16, v245
	v_and_b32_e32 v167, 0xffff0000, v245
	v_lshlrev_b32_e32 v168, 16, v246
	v_and_b32_e32 v169, 0xffff0000, v246
	v_lshlrev_b32_e32 v170, 16, v247
	v_and_b32_e32 v171, 0xffff0000, v247
	v_mul_f32_e32 v12, v12, v135
	v_mul_f32_e32 v13, v13, v135
	v_mul_f32_e32 v14, v14, v135
	v_mul_f32_e32 v15, v15, v135
	v_mul_f32_e32 v0, v0, v135
	v_mul_f32_e32 v1, v1, v135
	v_mul_f32_e32 v2, v2, v135
	v_mul_f32_e32 v3, v3, v135
	v_fmac_f32_e32 v164, v12, v148
	v_fmac_f32_e32 v165, v13, v149
	v_fmac_f32_e32 v166, v14, v150
	v_fmac_f32_e32 v167, v15, v151
	v_fmac_f32_e32 v168, v0, v152
	v_fmac_f32_e32 v169, v1, v153
	v_fmac_f32_e32 v170, v2, v154
	v_fmac_f32_e32 v171, v3, v155
	v_mul_f32_e32 v146, v164, v164
	v_fmac_f32_e32 v146, v165, v165
	v_fmac_f32_e32 v146, v166, v166
	v_fmac_f32_e32 v146, v167, v167
	v_fmac_f32_e32 v146, v168, v168
	v_fmac_f32_e32 v146, v169, v169
	v_fmac_f32_e32 v146, v170, v170
	v_fmac_f32_e32 v146, v171, v171
	v_cvt_pk_bf16_f32 v180, v164, v165
	v_cvt_pk_bf16_f32 v181, v166, v167
	v_cvt_pk_bf16_f32 v182, v168, v169
	v_cvt_pk_bf16_f32 v183, v170, v171
	global_store_dwordx4 v140, v[180:183], s[22:23]
	v_lshlrev_b32_e32 v172, 16, v248
	v_and_b32_e32 v173, 0xffff0000, v248
	v_lshlrev_b32_e32 v174, 16, v249
	v_and_b32_e32 v175, 0xffff0000, v249
	v_lshlrev_b32_e32 v176, 16, v250
	v_and_b32_e32 v177, 0xffff0000, v250
	v_lshlrev_b32_e32 v178, 16, v251
	v_and_b32_e32 v179, 0xffff0000, v251
	v_mul_f32_e32 v4, v4, v135
	v_mul_f32_e32 v5, v5, v135
	v_mul_f32_e32 v6, v6, v135
	v_mul_f32_e32 v7, v7, v135
	v_mul_f32_e32 v8, v8, v135
	v_mul_f32_e32 v9, v9, v135
	v_mul_f32_e32 v10, v10, v135
	v_mul_f32_e32 v11, v11, v135
	v_fmac_f32_e32 v172, v4, v156
	v_fmac_f32_e32 v173, v5, v157
	v_fmac_f32_e32 v174, v6, v158
	v_fmac_f32_e32 v175, v7, v159
	v_fmac_f32_e32 v176, v8, v160
	v_fmac_f32_e32 v177, v9, v161
	v_fmac_f32_e32 v178, v10, v162
	v_fmac_f32_e32 v179, v11, v163
	v_fmac_f32_e32 v146, v172, v172
	v_fmac_f32_e32 v146, v173, v173
	v_fmac_f32_e32 v146, v174, v174
	v_fmac_f32_e32 v146, v175, v175
	v_fmac_f32_e32 v146, v176, v176
	v_fmac_f32_e32 v146, v177, v177
	v_fmac_f32_e32 v146, v178, v178
	v_fmac_f32_e32 v146, v179, v179
	v_cvt_pk_bf16_f32 v184, v172, v173
	v_cvt_pk_bf16_f32 v185, v174, v175
	v_cvt_pk_bf16_f32 v186, v176, v177
	v_cvt_pk_bf16_f32 v187, v178, v179
	global_store_dwordx4 v140, v[184:187], s[22:23] offset:256
	v_mov_b32_e32 v148, v138
	v_mov_b32_e32 v149, v139
	v_mov_b32_e32 v150, v141
	v_mov_b32_e32 v151, v142
	v_mov_b32_e32 v152, v143
	v_mov_b32_e32 v153, v144
	v_mov_b32_e32 v154, v145
	v_mov_b32_e32 v155, v146
	v_xor_b32_e32 v138, 16, v137
	v_xor_b32_e32 v139, 32, v137
	v_lshlrev_b32_e32 v138, 2, v138
	v_lshlrev_b32_e32 v139, 2, v139
	ds_bpermute_b32 v164, v138, v148
	ds_bpermute_b32 v165, v138, v149
	ds_bpermute_b32 v166, v138, v150
	ds_bpermute_b32 v167, v138, v151
	ds_bpermute_b32 v168, v138, v152
	ds_bpermute_b32 v169, v138, v153
	ds_bpermute_b32 v170, v138, v154
	ds_bpermute_b32 v171, v138, v155
	s_waitcnt lgkmcnt(0)
	v_add_f32_e32 v148, v148, v164
	v_add_f32_e32 v149, v149, v165
	v_add_f32_e32 v150, v150, v166
	v_add_f32_e32 v151, v151, v167
	v_add_f32_e32 v152, v152, v168
	v_add_f32_e32 v153, v153, v169
	v_add_f32_e32 v154, v154, v170
	v_add_f32_e32 v155, v155, v171
	ds_bpermute_b32 v164, v139, v148
	ds_bpermute_b32 v165, v139, v149
	ds_bpermute_b32 v166, v139, v150
	ds_bpermute_b32 v167, v139, v151
	ds_bpermute_b32 v168, v139, v152
	ds_bpermute_b32 v169, v139, v153
	ds_bpermute_b32 v170, v139, v154
	ds_bpermute_b32 v171, v139, v155
	s_waitcnt lgkmcnt(0)
	v_add_f32_e32 v148, v148, v164
	v_add_f32_e32 v149, v149, v165
	v_add_f32_e32 v150, v150, v166
	v_add_f32_e32 v151, v151, v167
	v_add_f32_e32 v152, v152, v168
	v_add_f32_e32 v153, v153, v169
	v_add_f32_e32 v154, v154, v170
	v_add_f32_e32 v155, v155, v171
	s_and_b32 s98, s2, 7
	s_lshl_b32 s98, s98, 3
	s_bfe_u32 s99, s2, 0x30003
	s_or_b32 s98, s98, s99
	s_lshr_b32 s99, s2, 6
	s_mul_i32 s99, s99, 0x42000
	s_lshl_b32 s98, s98, 10
	s_add_u32 s100, s56, s99
	s_addc_u32 s101, s57, 0
	s_add_u32 s100, s100, s98
	s_addc_u32 s101, s101, 0
	v_lshrrev_b32_e32 v158, 8, v136
	v_bfe_u32 v159, v136, 6, 2
	v_and_b32_e32 v160, 15, v136
	v_lshl_add_u32 v160, v158, 6, v160
	v_mul_u32_u24_e32 v159, 0x4200, v159
	v_add_u32_e32 v160, v160, v159
	v_lshlrev_b32_e32 v160, 2, v160
	v_bfe_u32 v161, v136, 4, 2
	v_cmp_eq_u32_e32 vcc, 0, v161
	s_and_saveexec_b64 s[0:1], vcc
	global_store_dword v160, v148, s[100:101]
	global_store_dword v160, v149, s[100:101] offset:64
	global_store_dword v160, v150, s[100:101] offset:128
	global_store_dword v160, v151, s[100:101] offset:192
	global_store_dword v160, v152, s[100:101] offset:512
	global_store_dword v160, v153, s[100:101] offset:576
	global_store_dword v160, v154, s[100:101] offset:640
	global_store_dword v160, v155, s[100:101] offset:704
	s_or_b64 exec, exec, s[0:1]
	v_bfe_u32 v183, v136, 1, 2
	v_lshrrev_b32_e32 v187, 6, v136
	v_lshlrev_b32_e32 v190, 11, v136
	v_lshrrev_b32_e32 v252, 1, v136
	v_and_b32_e32 v132, 48, v136
	v_and_b32_e32 v189, 63, v136
	v_lshrrev_b32_e32 v182, 3, v136
	v_lshlrev_b32_e32 v188, 2, v136
	v_lshl_add_u32 v186, v183, 6, 0
	v_and_b32_e32 v191, 15, v136
	s_cmpk_lt_i32 s2, 0x420
	v_mov_b32_e32 v0, v136
	s_cselect_b64 s[8:9], -1, 0
	s_cmpk_gt_i32 s2, 0x41f
	s_cbranch_scc1 .LBB0_863
	v_and_b32_e32 v4, 63, v0
	v_ashrrev_i32_e32 v0, 5, v0
	v_readlane_b32 s12, v253, 3
	v_and_b32_e32 v5, -2, v0
	v_lshlrev_b32_e32 v0, 4, v4
	v_mov_b32_e32 v1, 0
	v_readlane_b32 s13, v253, 4
	s_mov_b64 s[0:1], 0x1000
	v_readlane_b32 s14, v253, 5
	v_lshl_add_u64 v[2:3], s[12:13], 0, v[0:1]
	v_lshl_add_u64 v[16:17], v[2:3], 0, s[0:1]
	v_and_b32_e32 v2, 64, v137
	v_add_u32_e32 v2, 64, v2
	v_xor_b32_e32 v3, 32, v137
	v_cmp_lt_i32_e64 s[0:1], v3, v2
	v_readlane_b32 s15, v253, 6
	v_readlane_b32 s16, v253, 7
	v_cndmask_b32_e64 v3, v137, v3, s[0:1]
	v_lshlrev_b32_e32 v50, 2, v3
	v_xor_b32_e32 v3, 16, v137
	v_cmp_lt_i32_e64 s[0:1], v3, v2
	v_readlane_b32 s17, v253, 8
	v_readlane_b32 s18, v253, 9
	v_cndmask_b32_e64 v3, v137, v3, s[0:1]
	v_lshlrev_b32_e32 v51, 2, v3
	v_xor_b32_e32 v3, 8, v137
	v_cmp_lt_i32_e64 s[0:1], v3, v2
	v_readlane_b32 s19, v253, 10
	v_readlane_b32 s20, v253, 11
	v_cndmask_b32_e64 v3, v137, v3, s[0:1]
	v_lshlrev_b32_e32 v52, 2, v3
	v_xor_b32_e32 v3, 4, v137
	v_cmp_lt_i32_e64 s[0:1], v3, v2
	v_readlane_b32 s21, v253, 12
	v_readlane_b32 s22, v253, 13
	v_cndmask_b32_e64 v3, v137, v3, s[0:1]
	v_lshlrev_b32_e32 v53, 2, v3
	v_xor_b32_e32 v3, 2, v137
	v_cmp_lt_i32_e64 s[0:1], v3, v2
	v_readlane_b32 s23, v253, 14
	v_readlane_b32 s24, v253, 15
	v_cndmask_b32_e64 v3, v137, v3, s[0:1]
	v_readlane_b32 s25, v253, 16
	v_readlane_b32 s26, v253, 17
	v_readlane_b32 s27, v253, 18
	v_mul_u32_u24_e32 v0, 0x4200, v4
	v_lshlrev_b32_e32 v54, 2, v3
	v_xor_b32_e32 v3, 1, v137
	v_cmp_lt_i32_e64 s[0:1], v3, v2
	v_lshlrev_b32_e32 v0, 2, v0
	v_readlane_b32 s12, v253, 51
	v_cndmask_b32_e64 v2, v137, v3, s[0:1]
	v_lshl_add_u64 v[18:19], s[44:45], 0, v[0:1]
	v_lshlrev_b32_e32 v0, 3, v4
	v_readlane_b32 s13, v253, 52
	v_readlane_b32 s14, v253, 53
	v_readlane_b32 s15, v253, 54
	v_cmp_gt_u32_e32 vcc, 16, v4
	v_lshlrev_b32_e32 v55, 2, v2
	v_cmp_eq_u32_e64 s[0:1], 0, v4
	v_lshl_add_u64 v[20:21], s[60:61], 0, v[0:1]
	v_lshl_add_u64 v[22:23], s[14:15], 0, v[0:1]
	v_lshl_add_u64 v[24:25], s[58:59], 0, v[0:1]
	v_lshl_add_u32 v26, s2, 4, v5
	s_lshl_b32 s3, s38, 4
	v_mov_b32_e32 v56, 0x358637bd
	s_mov_b32 s12, 0x800000
	s_mov_b32 s13, s2
	v_readlane_b32 s16, v253, 55
	v_readlane_b32 s17, v253, 56
	v_readlane_b32 s18, v253, 57
	v_readlane_b32 s19, v253, 58
	v_readlane_b32 s20, v253, 59
	v_readlane_b32 s21, v253, 60
	v_readlane_b32 s22, v253, 61
	v_readlane_b32 s23, v253, 62
	v_readlane_b32 s24, v253, 63
	v_readlane_b32 s25, v254, 0
	v_readlane_b32 s26, v254, 1
	v_readlane_b32 s27, v254, 2
	s_addk_i32 s13, 0x400
	v_add_u32_e32 v26, 0x4000, v26
	s_cmpk_lt_i32 s13, 0x420
	s_cbranch_scc0 .LBB0_863
	s_branch .LBB0_855

.LBB0_912:
	s_or_b64 exec, exec, s[6:7]
	s_mov_b64 s[6:7], exec
	v_mbcnt_lo_u32_b32 v0, s6, 0
	v_mbcnt_hi_u32_b32 v0, s7, v0
	v_cmp_eq_u32_e32 vcc, 0, v0
	s_and_saveexec_b64 s[12:13], vcc
	s_cbranch_execz .LBB0_914
	s_bcnt1_i32_b64 s3, s[6:7]
	v_mov_b32_e32 v0, 0x2000
	v_mov_b32_e32 v1, s3
	global_atomic_add v0, v1, s[4:5] offset:1024
.LBB0_914:
	s_or_b64 exec, exec, s[12:13]
.LBB0_915:
	s_or_b64 exec, exec, s[0:1]
	s_waitcnt lgkmcnt(0)
	v_cndmask_b32_e64 v0, 0, 1, s[10:11]
	v_cmp_ne_u32_e64 s[4:5], 1, v0
	s_andn2_b64 vcc, exec, s[10:11]
	s_barrier
	s_and_b32 s98, s2, 7
	s_lshl_b32 s98, s98, 3
	s_bfe_u32 s99, s2, 0x30003
	s_or_b32 s98, s98, s99
	s_lshr_b32 s99, s2, 6
	v_and_b32_e32 v140, 0xff, v136
	v_lshrrev_b32_e32 v141, 8, v136
	v_mul_u32_u24_e32 v141, 0x84000, v141
	v_lshl_add_u32 v140, v140, 2, v141
	s_lshl_b32 s24, s98, 10
	s_add_u32 s18, s56, s24
	s_addc_u32 s19, s57, 0
	global_load_dword v142, v140, s[18:19]
	s_add_u32 s18, s18, 0x10800
	s_addc_u32 s19, s19, 0
	global_load_dword v143, v140, s[18:19]
	s_add_u32 s18, s18, 0x10800
	s_addc_u32 s19, s19, 0
	global_load_dword v144, v140, s[18:19]
	s_add_u32 s18, s18, 0x10800
	s_addc_u32 s19, s19, 0
	global_load_dword v145, v140, s[18:19]
	s_add_u32 s18, s18, 0x10800
	s_addc_u32 s19, s19, 0
	global_load_dword v146, v140, s[18:19]
	s_add_u32 s18, s18, 0x10800
	s_addc_u32 s19, s19, 0
	global_load_dword v147, v140, s[18:19]
	s_add_u32 s18, s18, 0x10800
	s_addc_u32 s19, s19, 0
	global_load_dword v148, v140, s[18:19]
	s_add_u32 s18, s18, 0x10800
	s_addc_u32 s19, s19, 0
	global_load_dword v149, v140, s[18:19]
	s_waitcnt vmcnt(0)
	v_add_f32_e32 v142, v142, v143
	v_add_f32_e32 v142, v142, v144
	v_add_f32_e32 v142, v142, v145
	v_add_f32_e32 v142, v142, v146
	v_add_f32_e32 v142, v142, v147
	v_add_f32_e32 v142, v142, v148
	v_add_f32_e32 v142, v142, v149
	v_lshlrev_b32_e32 v141, 2, v136
	ds_write_b32 v141, v142 offset:0
	s_waitcnt lgkmcnt(0)
	s_barrier
	v_cmp_gt_u32_e32 vcc, 0x100, v136
	s_and_saveexec_b64 s[18:19], vcc
	ds_read_b32 v142, v141 offset:0
	ds_read_b32 v143, v141 offset:1024
	s_mov_b32 s25, 0x3a800000
	v_mov_b32_e32 v144, 0x358637bd
	s_waitcnt lgkmcnt(0)
	v_add_f32_e32 v142, v142, v143
	v_fma_f32 v142, v142, s25, v144
	v_rsq_f32_e32 v142, v142
	s_add_u32 s24, s46, s24
	s_addc_u32 s25, s47, 0
	s_nop 0
	global_store_dword v141, v142, s[24:25]
	s_or_b64 exec, exec, s[18:19]
	s_waitcnt vmcnt(0)
	s_barrier
	s_andn2_b64 vcc, exec, s[10:11]
	s_cbranch_vccnz .LBB0_920
	v_readlane_b32 s12, v253, 51
	v_and_b32_e32 v0, 0x7800, v190
	v_mov_b32_e32 v1, 0
	v_readlane_b32 s26, v254, 1
	v_readlane_b32 s27, v254, 2
	v_mov_b32_e32 v133, v1
	v_and_b32_e32 v7, 4, v188
	v_lshl_add_u64 v[2:3], s[26:27], 0, v[0:1]
	v_lshl_add_u64 v[4:5], v[2:3], 0, v[132:133]
	v_lshl_add_u64 v[2:3], s[60:61], 0, v[0:1]
	v_lshl_add_u64 v[2:3], v[2:3], 0, v[132:133]
	v_lshlrev_b32_e32 v0, 8, v187
	v_and_or_b32 v6, v182, 16, v7
	v_readlane_b32 s14, v253, 53
	v_readlane_b32 s15, v253, 54
	v_readlane_b32 s16, v253, 55
	v_readlane_b32 s17, v253, 56
	v_readlane_b32 s18, v253, 57
	v_readlane_b32 s19, v253, 58
	v_readlane_b32 s20, v253, 59
	v_readlane_b32 s21, v253, 60
	v_readlane_b32 s22, v253, 61
	v_lshl_add_u64 v[2:3], v[2:3], 0, v[0:1]
	v_lshl_add_u64 v[4:5], v[4:5], 0, v[0:1]
	v_lshlrev_b32_e32 v0, 13, v187
	v_lshl_add_u32 v8, v189, 2, 0
	s_movk_i32 s0, 0x100
	v_and_b32_e32 v9, 60, v252
	v_lshlrev_b32_e32 v6, 8, v6
	s_mov_b32 s7, 0
	v_cmp_gt_u32_e32 vcc, s0, v136
	v_add3_u32 v6, v186, v9, v6
	v_lshl_or_b32 v7, v183, 3, v7
	s_lshl_b32 s3, s2, 1
	s_lshl_b32 s14, s38, 1
	s_lshl_b32 s15, s2, 2
	s_lshl_b32 s16, s38, 2
	s_lshl_b32 s17, s2, 5
	s_lshl_b32 s18, s38, 5
	s_mov_b32 s19, 0x8000
	s_mov_b32 s20, 0x40000
	s_mov_b32 s21, 0x48000
	v_add_u32_e32 v8, v8, v0
	s_mov_b32 s22, s2
	v_readlane_b32 s13, v253, 52
	v_readlane_b32 s23, v253, 62
	v_readlane_b32 s24, v253, 63
	v_readlane_b32 s25, v254, 0
	s_branch .LBB0_918

.LBB0_979:
	s_or_b64 exec, exec, s[12:13]
	s_mov_b64 s[12:13], exec
	v_mbcnt_lo_u32_b32 v0, s12, 0
	v_mbcnt_hi_u32_b32 v0, s13, v0
	v_cmp_eq_u32_e32 vcc, 0, v0
	s_and_saveexec_b64 s[14:15], vcc
	s_cbranch_execz .LBB0_981
	s_bcnt1_i32_b64 s3, s[12:13]
	v_mov_b32_e32 v0, 0x2000
	v_mov_b32_e32 v1, s3
	global_atomic_add v0, v1, s[6:7] offset:1024
.LBB0_981:
	s_or_b64 exec, exec, s[14:15]
.LBB0_982:
	s_or_b64 exec, exec, s[0:1]
	s_bitcmp0_b32 s2, 3
	s_cselect_b64 s[12:13], -1, 0
	s_cmpk_gt_i32 s2, 0xff
	s_cselect_b64 s[0:1], -1, 0
	s_or_b64 s[0:1], s[0:1], s[12:13]
	s_mov_b32 s3, 0
	s_and_b64 vcc, exec, s[0:1]
	s_waitcnt lgkmcnt(0)
	s_barrier
	s_cbranch_vccnz .LBB0_1025
	s_lshl_b64 s[0:1], s[2:3], 17
	s_add_u32 s0, s68, s0
	s_addc_u32 s1, s69, s1
	s_add_u32 s6, s0, 0x10000
	s_addc_u32 s7, s1, 0
	s_add_u32 s14, s0, 0x10080
	s_addc_u32 s15, s1, 0
	s_add_u32 s16, s0, 0x10100
	s_addc_u32 s17, s1, 0
	s_add_u32 s18, s0, 0x10180
	s_addc_u32 s19, s1, 0
	s_lshl_b32 s3, s2, 8
	s_lshl_b32 s36, s38, 8
	s_movk_i32 s37, 0xfa00
	v_mov_b32_e32 v129, 0
	s_add_i32 s40, 0, 0x18000
	s_mov_b64 s[20:21], 0x80
	s_add_i32 s41, 0, 0x1c000
	s_mov_b64 s[22:23], 0x100
	s_mov_b64 s[24:25], 0x180
	s_mov_b32 s46, 0xff61b1e6
	v_mov_b32_e32 v133, 1
	s_mov_b32 s47, s2
	s_branch .LBB0_985

.LBB0_1156:
	s_or_b64 exec, exec, s[10:11]
	s_mov_b64 s[10:11], exec
	v_mbcnt_lo_u32_b32 v0, s10, 0
	v_mbcnt_hi_u32_b32 v0, s11, v0
	v_cmp_eq_u32_e32 vcc, 0, v0
	s_and_saveexec_b64 s[12:13], vcc
	s_cbranch_execz .LBB0_1158
	s_bcnt1_i32_b64 s3, s[10:11]
	v_mov_b32_e32 v0, 0x2000
	v_mov_b32_e32 v1, s3
	global_atomic_add v0, v1, s[6:7] offset:1024
.LBB0_1158:
	s_or_b64 exec, exec, s[12:13]
.LBB0_1159:
	s_or_b64 exec, exec, s[0:1]
	s_and_b64 vcc, exec, s[4:5]
	s_waitcnt lgkmcnt(0)
	s_barrier
	s_cbranch_vccnz .LBB0_1165
	v_readlane_b32 s12, v254, 4
	v_and_b32_e32 v0, 0x7800, v190
	v_mov_b32_e32 v1, 0
	v_readlane_b32 s13, v254, 5
	v_mov_b32_e32 v133, v1
	v_and_b32_e32 v7, 4, v188
	v_lshl_add_u64 v[2:3], s[12:13], 0, v[0:1]
	v_lshl_add_u64 v[4:5], v[2:3], 0, v[132:133]
	v_lshl_add_u64 v[2:3], s[70:71], 0, v[0:1]
	v_and_or_b32 v6, v182, 16, v7
	v_lshl_add_u64 v[2:3], v[2:3], 0, v[132:133]
	v_lshlrev_b32_e32 v0, 8, v187
	v_and_b32_e32 v9, 60, v252
	v_lshlrev_b32_e32 v6, 8, v6
	v_readlane_b32 s16, v254, 8
	v_readlane_b32 s17, v254, 9
	v_readlane_b32 s18, v254, 10
	v_readlane_b32 s19, v254, 11
	v_readlane_b32 s20, v254, 12
	v_lshl_add_u64 v[2:3], v[2:3], 0, v[0:1]
	v_lshl_add_u64 v[4:5], v[4:5], 0, v[0:1]
	v_lshlrev_b32_e32 v0, 13, v187
	v_lshl_add_u32 v8, v189, 2, 0
	s_movk_i32 s0, 0x100
	v_add3_u32 v6, v186, v9, v6
	v_and_b32_e32 v9, 7, v136
	s_mov_b32 s11, 0
	v_cmp_gt_u32_e32 vcc, s0, v136
	v_lshl_or_b32 v7, v183, 3, v7
	v_cmp_eq_u32_e64 s[0:1], 0, v9
	s_lshl_b32 s3, s2, 5
	s_lshl_b32 s16, s38, 5
	s_mov_b32 s17, 0x8000
	s_mov_b32 s18, 0x40000
	s_mov_b32 s19, 0x48000
	v_add_u32_e32 v8, v8, v0
	s_mov_b32 s20, s2
	v_readlane_b32 s14, v254, 6
	v_readlane_b32 s15, v254, 7
	v_readlane_b32 s21, v254, 13
	v_readlane_b32 s22, v254, 14
	v_readlane_b32 s23, v254, 15
	v_readlane_b32 s24, v254, 16
	v_readlane_b32 s25, v254, 17
	v_readlane_b32 s26, v254, 18
	v_readlane_b32 s27, v254, 19
	s_branch .LBB0_1162

.LBB0_1240:
	s_or_b64 exec, exec, s[10:11]
	s_mov_b64 s[10:11], exec
	v_mbcnt_lo_u32_b32 v140, s10, 0
	v_mbcnt_hi_u32_b32 v140, s11, v140
	v_cmp_eq_u32_e32 vcc, 0, v140
	s_and_saveexec_b64 s[12:13], vcc
	s_cbranch_execz .LBB0_1242
	s_bcnt1_i32_b64 s3, s[10:11]
	v_mov_b32_e32 v140, 0x2000
	v_mov_b32_e32 v141, s3
	global_atomic_add v140, v141, s[6:7] offset:1024
.LBB0_1242:
	s_or_b64 exec, exec, s[12:13]
.LBB0_1243:
	s_or_b64 exec, exec, s[0:1]
	s_waitcnt lgkmcnt(0)
	s_barrier
	s_and_b32 s98, s2, 7
	s_lshl_b32 s98, s98, 3
	s_bfe_u32 s99, s2, 0x30003
	s_or_b32 s98, s98, s99
	s_lshr_b32 s99, s2, 6
	v_and_b32_e32 v172, 0xff, v136
	v_lshrrev_b32_e32 v173, 8, v136
	v_mul_u32_u24_e32 v173, 0x84000, v173
	v_lshl_add_u32 v172, v172, 2, v173
	s_lshl_b32 s24, s98, 10
	s_add_u32 s18, s44, s24
	s_addc_u32 s19, s45, 0
	global_load_dword v164, v172, s[18:19]
	s_add_u32 s18, s18, 0x10800
	s_addc_u32 s19, s19, 0
	global_load_dword v165, v172, s[18:19]
	s_add_u32 s18, s18, 0x10800
	s_addc_u32 s19, s19, 0
	global_load_dword v166, v172, s[18:19]
	s_add_u32 s18, s18, 0x10800
	s_addc_u32 s19, s19, 0
	global_load_dword v167, v172, s[18:19]
	s_add_u32 s18, s18, 0x10800
	s_addc_u32 s19, s19, 0
	global_load_dword v168, v172, s[18:19]
	s_add_u32 s18, s18, 0x10800
	s_addc_u32 s19, s19, 0
	global_load_dword v169, v172, s[18:19]
	s_add_u32 s18, s18, 0x10800
	s_addc_u32 s19, s19, 0
	global_load_dword v170, v172, s[18:19]
	s_add_u32 s18, s18, 0x10800
	s_addc_u32 s19, s19, 0
	global_load_dword v171, v172, s[18:19]
	v_lshrrev_b32_e32 v141, 8, v136
	v_and_b32_e32 v142, 15, v136
	v_lshl_add_u32 v141, v141, 6, v142
	v_bfe_u32 v144, v136, 6, 2
	v_bfe_u32 v145, v136, 4, 2
	v_lshlrev_b32_e32 v144, 5, v144
	v_lshl_add_u32 v144, v145, 3, v144
	s_lshl_b32 s24, s99, 8
	v_add_u32_e32 v144, s24, v144
	s_lshl_b32 s25, s98, 8
	v_add_u32_e32 v145, s25, v141
	v_lshl_add_u32 v146, v145, 10, v144
	v_lshlrev_b32_e32 v140, 1, v146
	v_lshlrev_b32_e32 v147, 2, v144
	v_readlane_b32 s18, v253, 3
	v_readlane_b32 s19, v253, 4
	s_mov_b32 s20, s60
	s_mov_b32 s21, s61
	s_nop 4
	s_add_u32 s18, s18, 0x3000
	s_addc_u32 s19, s19, 0
	global_load_dwordx4 v[148:151], v147, s[18:19]
	global_load_dwordx4 v[152:155], v147, s[18:19] offset:16
	global_load_dwordx4 v[156:159], v147, s[18:19] offset:512
	global_load_dwordx4 v[160:163], v147, s[18:19] offset:528
	s_add_u32 s22, s20, 0x0
	s_addc_u32 s23, s21, 0
	global_load_dwordx4 v[188:191], v140, s[22:23] nt
	global_load_dwordx4 v[192:195], v140, s[22:23] offset:256 nt
	s_add_u32 s22, s20, 0x8000
	s_addc_u32 s23, s21, 0
	global_load_dwordx4 v[196:199], v140, s[22:23] nt
	global_load_dwordx4 v[200:203], v140, s[22:23] offset:256 nt
	s_add_u32 s22, s20, 0x10000
	s_addc_u32 s23, s21, 0
	global_load_dwordx4 v[204:207], v140, s[22:23] nt
	global_load_dwordx4 v[208:211], v140, s[22:23] offset:256 nt
	s_add_u32 s22, s20, 0x18000
	s_addc_u32 s23, s21, 0
	global_load_dwordx4 v[212:215], v140, s[22:23] nt
	global_load_dwordx4 v[216:219], v140, s[22:23] offset:256 nt
	s_add_u32 s22, s20, 0x40000
	s_addc_u32 s23, s21, 0
	global_load_dwordx4 v[220:223], v140, s[22:23] nt
	global_load_dwordx4 v[224:227], v140, s[22:23] offset:256 nt
	s_add_u32 s22, s20, 0x48000
	s_addc_u32 s23, s21, 0
	global_load_dwordx4 v[228:231], v140, s[22:23] nt
	global_load_dwordx4 v[232:235], v140, s[22:23] offset:256 nt
	s_add_u32 s22, s20, 0x50000
	s_addc_u32 s23, s21, 0
	global_load_dwordx4 v[236:239], v140, s[22:23] nt
	global_load_dwordx4 v[240:243], v140, s[22:23] offset:256 nt
	s_add_u32 s22, s20, 0x58000
	s_addc_u32 s23, s21, 0
	global_load_dwordx4 v[244:247], v140, s[22:23] nt
	global_load_dwordx4 v[248:251], v140, s[22:23] offset:256 nt
	s_waitcnt vmcnt(20)
	v_add_f32_e32 v164, v164, v165
	v_add_f32_e32 v164, v164, v166
	v_add_f32_e32 v164, v164, v167
	v_add_f32_e32 v164, v164, v168
	v_add_f32_e32 v164, v164, v169
	v_add_f32_e32 v164, v164, v170
	v_add_f32_e32 v164, v164, v171
	v_lshlrev_b32_e32 v173, 2, v136
	ds_write_b32 v173, v164
	s_waitcnt lgkmcnt(0)
	s_barrier
	v_lshlrev_b32_e32 v142, 2, v141
	ds_read_b32 v128, v142 offset:0
	ds_read_b32 v174, v142 offset:1024
	ds_read_b32 v129, v142 offset:64
	ds_read_b32 v175, v142 offset:1088
	ds_read_b32 v130, v142 offset:128
	ds_read_b32 v176, v142 offset:1152
	ds_read_b32 v131, v142 offset:192
	ds_read_b32 v177, v142 offset:1216
	ds_read_b32 v132, v142 offset:512
	ds_read_b32 v178, v142 offset:1536
	ds_read_b32 v133, v142 offset:576
	ds_read_b32 v179, v142 offset:1600
	ds_read_b32 v134, v142 offset:640
	ds_read_b32 v180, v142 offset:1664
	ds_read_b32 v135, v142 offset:704
	ds_read_b32 v181, v142 offset:1728
	s_waitcnt lgkmcnt(0)
	s_mov_b32 s101, 0x3a800000
	v_mov_b32_e32 v143, 0x358637bd
	v_add_f32_e32 v128, v128, v174
	v_add_f32_e32 v129, v129, v175
	v_add_f32_e32 v130, v130, v176
	v_add_f32_e32 v131, v131, v177
	v_add_f32_e32 v132, v132, v178
	v_add_f32_e32 v133, v133, v179
	v_add_f32_e32 v134, v134, v180
	v_add_f32_e32 v135, v135, v181
	v_fma_f32 v128, v128, s101, v143
	v_fma_f32 v129, v129, s101, v143
	v_fma_f32 v130, v130, s101, v143
	v_fma_f32 v131, v131, s101, v143
	v_fma_f32 v132, v132, s101, v143
	v_fma_f32 v133, v133, s101, v143
	v_fma_f32 v134, v134, s101, v143
	v_fma_f32 v135, v135, s101, v143
	v_rsq_f32_e32 v128, v128
	v_rsq_f32_e32 v129, v129
	v_rsq_f32_e32 v130, v130
	v_rsq_f32_e32 v131, v131
	v_rsq_f32_e32 v132, v132
	v_rsq_f32_e32 v133, v133
	v_rsq_f32_e32 v134, v134
	v_rsq_f32_e32 v135, v135
	s_waitcnt vmcnt(0)
	s_add_u32 s22, s64, 0x0
	s_addc_u32 s23, s65, 0
	v_lshlrev_b32_e32 v164, 16, v188
	v_and_b32_e32 v165, 0xffff0000, v188
	v_lshlrev_b32_e32 v166, 16, v189
	v_and_b32_e32 v167, 0xffff0000, v189
	v_lshlrev_b32_e32 v168, 16, v190
	v_and_b32_e32 v169, 0xffff0000, v190
	v_lshlrev_b32_e32 v170, 16, v191
	v_and_b32_e32 v171, 0xffff0000, v191
	v_mul_f32_e32 v124, v124, v128
	v_mul_f32_e32 v125, v125, v128
	v_mul_f32_e32 v126, v126, v128
	v_mul_f32_e32 v127, v127, v128
	v_mul_f32_e32 v112, v112, v128
	v_mul_f32_e32 v113, v113, v128
	v_mul_f32_e32 v114, v114, v128
	v_mul_f32_e32 v115, v115, v128
	v_fmac_f32_e32 v164, v124, v148
	v_fmac_f32_e32 v165, v125, v149
	v_fmac_f32_e32 v166, v126, v150
	v_fmac_f32_e32 v167, v127, v151
	v_fmac_f32_e32 v168, v112, v152
	v_fmac_f32_e32 v169, v113, v153
	v_fmac_f32_e32 v170, v114, v154
	v_fmac_f32_e32 v171, v115, v155
	v_mul_f32_e32 v138, v164, v164
	v_fmac_f32_e32 v138, v165, v165
	v_fmac_f32_e32 v138, v166, v166
	v_fmac_f32_e32 v138, v167, v167
	v_fmac_f32_e32 v138, v168, v168
	v_fmac_f32_e32 v138, v169, v169
	v_fmac_f32_e32 v138, v170, v170
	v_fmac_f32_e32 v138, v171, v171
	v_cvt_pk_bf16_f32 v180, v164, v165
	v_cvt_pk_bf16_f32 v181, v166, v167
	v_cvt_pk_bf16_f32 v182, v168, v169
	v_cvt_pk_bf16_f32 v183, v170, v171
	global_store_dwordx4 v140, v[180:183], s[22:23]
	v_lshlrev_b32_e32 v172, 16, v192
	v_and_b32_e32 v173, 0xffff0000, v192
	v_lshlrev_b32_e32 v174, 16, v193
	v_and_b32_e32 v175, 0xffff0000, v193
	v_lshlrev_b32_e32 v176, 16, v194
	v_and_b32_e32 v177, 0xffff0000, v194
	v_lshlrev_b32_e32 v178, 16, v195
	v_and_b32_e32 v179, 0xffff0000, v195
	v_mul_f32_e32 v120, v120, v128
	v_mul_f32_e32 v121, v121, v128
	v_mul_f32_e32 v122, v122, v128
	v_mul_f32_e32 v123, v123, v128
	v_mul_f32_e32 v116, v116, v128
	v_mul_f32_e32 v117, v117, v128
	v_mul_f32_e32 v118, v118, v128
	v_mul_f32_e32 v119, v119, v128
	v_fmac_f32_e32 v172, v120, v156
	v_fmac_f32_e32 v173, v121, v157
	v_fmac_f32_e32 v174, v122, v158
	v_fmac_f32_e32 v175, v123, v159
	v_fmac_f32_e32 v176, v116, v160
	v_fmac_f32_e32 v177, v117, v161
	v_fmac_f32_e32 v178, v118, v162
	v_fmac_f32_e32 v179, v119, v163
	v_fmac_f32_e32 v138, v172, v172
	v_fmac_f32_e32 v138, v173, v173
	v_fmac_f32_e32 v138, v174, v174
	v_fmac_f32_e32 v138, v175, v175
	v_fmac_f32_e32 v138, v176, v176
	v_fmac_f32_e32 v138, v177, v177
	v_fmac_f32_e32 v138, v178, v178
	v_fmac_f32_e32 v138, v179, v179
	v_cvt_pk_bf16_f32 v184, v172, v173
	v_cvt_pk_bf16_f32 v185, v174, v175
	v_cvt_pk_bf16_f32 v186, v176, v177
	v_cvt_pk_bf16_f32 v187, v178, v179
	global_store_dwordx4 v140, v[184:187], s[22:23] offset:256
	s_add_u32 s22, s64, 0x8000
	s_addc_u32 s23, s65, 0
	v_lshlrev_b32_e32 v164, 16, v196
	v_and_b32_e32 v165, 0xffff0000, v196
	v_lshlrev_b32_e32 v166, 16, v197
	v_and_b32_e32 v167, 0xffff0000, v197
	v_lshlrev_b32_e32 v168, 16, v198
	v_and_b32_e32 v169, 0xffff0000, v198
	v_lshlrev_b32_e32 v170, 16, v199
	v_and_b32_e32 v171, 0xffff0000, v199
	v_mul_f32_e32 v108, v108, v129
	v_mul_f32_e32 v109, v109, v129
	v_mul_f32_e32 v110, v110, v129
	v_mul_f32_e32 v111, v111, v129
	v_mul_f32_e32 v96, v96, v129
	v_mul_f32_e32 v97, v97, v129
	v_mul_f32_e32 v98, v98, v129
	v_mul_f32_e32 v99, v99, v129
	v_fmac_f32_e32 v164, v108, v148
	v_fmac_f32_e32 v165, v109, v149
	v_fmac_f32_e32 v166, v110, v150
	v_fmac_f32_e32 v167, v111, v151
	v_fmac_f32_e32 v168, v96, v152
	v_fmac_f32_e32 v169, v97, v153
	v_fmac_f32_e32 v170, v98, v154
	v_fmac_f32_e32 v171, v99, v155
	v_mul_f32_e32 v139, v164, v164
	v_fmac_f32_e32 v139, v165, v165
	v_fmac_f32_e32 v139, v166, v166
	v_fmac_f32_e32 v139, v167, v167
	v_fmac_f32_e32 v139, v168, v168
	v_fmac_f32_e32 v139, v169, v169
	v_fmac_f32_e32 v139, v170, v170
	v_fmac_f32_e32 v139, v171, v171
	v_cvt_pk_bf16_f32 v180, v164, v165
	v_cvt_pk_bf16_f32 v181, v166, v167
	v_cvt_pk_bf16_f32 v182, v168, v169
	v_cvt_pk_bf16_f32 v183, v170, v171
	global_store_dwordx4 v140, v[180:183], s[22:23]
	v_lshlrev_b32_e32 v172, 16, v200
	v_and_b32_e32 v173, 0xffff0000, v200
	v_lshlrev_b32_e32 v174, 16, v201
	v_and_b32_e32 v175, 0xffff0000, v201
	v_lshlrev_b32_e32 v176, 16, v202
	v_and_b32_e32 v177, 0xffff0000, v202
	v_lshlrev_b32_e32 v178, 16, v203
	v_and_b32_e32 v179, 0xffff0000, v203
	v_mul_f32_e32 v100, v100, v129
	v_mul_f32_e32 v101, v101, v129
	v_mul_f32_e32 v102, v102, v129
	v_mul_f32_e32 v103, v103, v129
	v_mul_f32_e32 v104, v104, v129
	v_mul_f32_e32 v105, v105, v129
	v_mul_f32_e32 v106, v106, v129
	v_mul_f32_e32 v107, v107, v129
	v_fmac_f32_e32 v172, v100, v156
	v_fmac_f32_e32 v173, v101, v157
	v_fmac_f32_e32 v174, v102, v158
	v_fmac_f32_e32 v175, v103, v159
	v_fmac_f32_e32 v176, v104, v160
	v_fmac_f32_e32 v177, v105, v161
	v_fmac_f32_e32 v178, v106, v162
	v_fmac_f32_e32 v179, v107, v163
	v_fmac_f32_e32 v139, v172, v172
	v_fmac_f32_e32 v139, v173, v173
	v_fmac_f32_e32 v139, v174, v174
	v_fmac_f32_e32 v139, v175, v175
	v_fmac_f32_e32 v139, v176, v176
	v_fmac_f32_e32 v139, v177, v177
	v_fmac_f32_e32 v139, v178, v178
	v_fmac_f32_e32 v139, v179, v179
	v_cvt_pk_bf16_f32 v184, v172, v173
	v_cvt_pk_bf16_f32 v185, v174, v175
	v_cvt_pk_bf16_f32 v186, v176, v177
	v_cvt_pk_bf16_f32 v187, v178, v179
	global_store_dwordx4 v140, v[184:187], s[22:23] offset:256
	s_add_u32 s22, s64, 0x10000
	s_addc_u32 s23, s65, 0
	v_lshlrev_b32_e32 v164, 16, v204
	v_and_b32_e32 v165, 0xffff0000, v204
	v_lshlrev_b32_e32 v166, 16, v205
	v_and_b32_e32 v167, 0xffff0000, v205
	v_lshlrev_b32_e32 v168, 16, v206
	v_and_b32_e32 v169, 0xffff0000, v206
	v_lshlrev_b32_e32 v170, 16, v207
	v_and_b32_e32 v171, 0xffff0000, v207
	v_mul_f32_e32 v92, v92, v130
	v_mul_f32_e32 v93, v93, v130
	v_mul_f32_e32 v94, v94, v130
	v_mul_f32_e32 v95, v95, v130
	v_mul_f32_e32 v80, v80, v130
	v_mul_f32_e32 v81, v81, v130
	v_mul_f32_e32 v82, v82, v130
	v_mul_f32_e32 v83, v83, v130
	v_fmac_f32_e32 v164, v92, v148
	v_fmac_f32_e32 v165, v93, v149
	v_fmac_f32_e32 v166, v94, v150
	v_fmac_f32_e32 v167, v95, v151
	v_fmac_f32_e32 v168, v80, v152
	v_fmac_f32_e32 v169, v81, v153
	v_fmac_f32_e32 v170, v82, v154
	v_fmac_f32_e32 v171, v83, v155
	v_mul_f32_e32 v141, v164, v164
	v_fmac_f32_e32 v141, v165, v165
	v_fmac_f32_e32 v141, v166, v166
	v_fmac_f32_e32 v141, v167, v167
	v_fmac_f32_e32 v141, v168, v168
	v_fmac_f32_e32 v141, v169, v169
	v_fmac_f32_e32 v141, v170, v170
	v_fmac_f32_e32 v141, v171, v171
	v_cvt_pk_bf16_f32 v180, v164, v165
	v_cvt_pk_bf16_f32 v181, v166, v167
	v_cvt_pk_bf16_f32 v182, v168, v169
	v_cvt_pk_bf16_f32 v183, v170, v171
	global_store_dwordx4 v140, v[180:183], s[22:23]
	v_lshlrev_b32_e32 v172, 16, v208
	v_and_b32_e32 v173, 0xffff0000, v208
	v_lshlrev_b32_e32 v174, 16, v209
	v_and_b32_e32 v175, 0xffff0000, v209
	v_lshlrev_b32_e32 v176, 16, v210
	v_and_b32_e32 v177, 0xffff0000, v210
	v_lshlrev_b32_e32 v178, 16, v211
	v_and_b32_e32 v179, 0xffff0000, v211
	v_mul_f32_e32 v84, v84, v130
	v_mul_f32_e32 v85, v85, v130
	v_mul_f32_e32 v86, v86, v130
	v_mul_f32_e32 v87, v87, v130
	v_mul_f32_e32 v88, v88, v130
	v_mul_f32_e32 v89, v89, v130
	v_mul_f32_e32 v90, v90, v130
	v_mul_f32_e32 v91, v91, v130
	v_fmac_f32_e32 v172, v84, v156
	v_fmac_f32_e32 v173, v85, v157
	v_fmac_f32_e32 v174, v86, v158
	v_fmac_f32_e32 v175, v87, v159
	v_fmac_f32_e32 v176, v88, v160
	v_fmac_f32_e32 v177, v89, v161
	v_fmac_f32_e32 v178, v90, v162
	v_fmac_f32_e32 v179, v91, v163
	v_fmac_f32_e32 v141, v172, v172
	v_fmac_f32_e32 v141, v173, v173
	v_fmac_f32_e32 v141, v174, v174
	v_fmac_f32_e32 v141, v175, v175
	v_fmac_f32_e32 v141, v176, v176
	v_fmac_f32_e32 v141, v177, v177
	v_fmac_f32_e32 v141, v178, v178
	v_fmac_f32_e32 v141, v179, v179
	v_cvt_pk_bf16_f32 v184, v172, v173
	v_cvt_pk_bf16_f32 v185, v174, v175
	v_cvt_pk_bf16_f32 v186, v176, v177
	v_cvt_pk_bf16_f32 v187, v178, v179
	global_store_dwordx4 v140, v[184:187], s[22:23] offset:256
	s_add_u32 s22, s64, 0x18000
	s_addc_u32 s23, s65, 0
	v_lshlrev_b32_e32 v164, 16, v212
	v_and_b32_e32 v165, 0xffff0000, v212
	v_lshlrev_b32_e32 v166, 16, v213
	v_and_b32_e32 v167, 0xffff0000, v213
	v_lshlrev_b32_e32 v168, 16, v214
	v_and_b32_e32 v169, 0xffff0000, v214
	v_lshlrev_b32_e32 v170, 16, v215
	v_and_b32_e32 v171, 0xffff0000, v215
	v_mul_f32_e32 v76, v76, v131
	v_mul_f32_e32 v77, v77, v131
	v_mul_f32_e32 v78, v78, v131
	v_mul_f32_e32 v79, v79, v131
	v_mul_f32_e32 v64, v64, v131
	v_mul_f32_e32 v65, v65, v131
	v_mul_f32_e32 v66, v66, v131
	v_mul_f32_e32 v67, v67, v131
	v_fmac_f32_e32 v164, v76, v148
	v_fmac_f32_e32 v165, v77, v149
	v_fmac_f32_e32 v166, v78, v150
	v_fmac_f32_e32 v167, v79, v151
	v_fmac_f32_e32 v168, v64, v152
	v_fmac_f32_e32 v169, v65, v153
	v_fmac_f32_e32 v170, v66, v154
	v_fmac_f32_e32 v171, v67, v155
	v_mul_f32_e32 v142, v164, v164
	v_fmac_f32_e32 v142, v165, v165
	v_fmac_f32_e32 v142, v166, v166
	v_fmac_f32_e32 v142, v167, v167
	v_fmac_f32_e32 v142, v168, v168
	v_fmac_f32_e32 v142, v169, v169
	v_fmac_f32_e32 v142, v170, v170
	v_fmac_f32_e32 v142, v171, v171
	v_cvt_pk_bf16_f32 v180, v164, v165
	v_cvt_pk_bf16_f32 v181, v166, v167
	v_cvt_pk_bf16_f32 v182, v168, v169
	v_cvt_pk_bf16_f32 v183, v170, v171
	global_store_dwordx4 v140, v[180:183], s[22:23]
	v_lshlrev_b32_e32 v172, 16, v216
	v_and_b32_e32 v173, 0xffff0000, v216
	v_lshlrev_b32_e32 v174, 16, v217
	v_and_b32_e32 v175, 0xffff0000, v217
	v_lshlrev_b32_e32 v176, 16, v218
	v_and_b32_e32 v177, 0xffff0000, v218
	v_lshlrev_b32_e32 v178, 16, v219
	v_and_b32_e32 v179, 0xffff0000, v219
	v_mul_f32_e32 v68, v68, v131
	v_mul_f32_e32 v69, v69, v131
	v_mul_f32_e32 v70, v70, v131
	v_mul_f32_e32 v71, v71, v131
	v_mul_f32_e32 v72, v72, v131
	v_mul_f32_e32 v73, v73, v131
	v_mul_f32_e32 v74, v74, v131
	v_mul_f32_e32 v75, v75, v131
	v_fmac_f32_e32 v172, v68, v156
	v_fmac_f32_e32 v173, v69, v157
	v_fmac_f32_e32 v174, v70, v158
	v_fmac_f32_e32 v175, v71, v159
	v_fmac_f32_e32 v176, v72, v160
	v_fmac_f32_e32 v177, v73, v161
	v_fmac_f32_e32 v178, v74, v162
	v_fmac_f32_e32 v179, v75, v163
	v_fmac_f32_e32 v142, v172, v172
	v_fmac_f32_e32 v142, v173, v173
	v_fmac_f32_e32 v142, v174, v174
	v_fmac_f32_e32 v142, v175, v175
	v_fmac_f32_e32 v142, v176, v176
	v_fmac_f32_e32 v142, v177, v177
	v_fmac_f32_e32 v142, v178, v178
	v_fmac_f32_e32 v142, v179, v179
	v_cvt_pk_bf16_f32 v184, v172, v173
	v_cvt_pk_bf16_f32 v185, v174, v175
	v_cvt_pk_bf16_f32 v186, v176, v177
	v_cvt_pk_bf16_f32 v187, v178, v179
	global_store_dwordx4 v140, v[184:187], s[22:23] offset:256
	s_add_u32 s22, s64, 0x40000
	s_addc_u32 s23, s65, 0
	v_lshlrev_b32_e32 v164, 16, v220
	v_and_b32_e32 v165, 0xffff0000, v220
	v_lshlrev_b32_e32 v166, 16, v221
	v_and_b32_e32 v167, 0xffff0000, v221
	v_lshlrev_b32_e32 v168, 16, v222
	v_and_b32_e32 v169, 0xffff0000, v222
	v_lshlrev_b32_e32 v170, 16, v223
	v_and_b32_e32 v171, 0xffff0000, v223
	v_mul_f32_e32 v60, v60, v132
	v_mul_f32_e32 v61, v61, v132
	v_mul_f32_e32 v62, v62, v132
	v_mul_f32_e32 v63, v63, v132
	v_mul_f32_e32 v48, v48, v132
	v_mul_f32_e32 v49, v49, v132
	v_mul_f32_e32 v50, v50, v132
	v_mul_f32_e32 v51, v51, v132
	v_fmac_f32_e32 v164, v60, v148
	v_fmac_f32_e32 v165, v61, v149
	v_fmac_f32_e32 v166, v62, v150
	v_fmac_f32_e32 v167, v63, v151
	v_fmac_f32_e32 v168, v48, v152
	v_fmac_f32_e32 v169, v49, v153
	v_fmac_f32_e32 v170, v50, v154
	v_fmac_f32_e32 v171, v51, v155
	v_mul_f32_e32 v143, v164, v164
	v_fmac_f32_e32 v143, v165, v165
	v_fmac_f32_e32 v143, v166, v166
	v_fmac_f32_e32 v143, v167, v167
	v_fmac_f32_e32 v143, v168, v168
	v_fmac_f32_e32 v143, v169, v169
	v_fmac_f32_e32 v143, v170, v170
	v_fmac_f32_e32 v143, v171, v171
	v_cvt_pk_bf16_f32 v180, v164, v165
	v_cvt_pk_bf16_f32 v181, v166, v167
	v_cvt_pk_bf16_f32 v182, v168, v169
	v_cvt_pk_bf16_f32 v183, v170, v171
	global_store_dwordx4 v140, v[180:183], s[22:23]
	v_lshlrev_b32_e32 v172, 16, v224
	v_and_b32_e32 v173, 0xffff0000, v224
	v_lshlrev_b32_e32 v174, 16, v225
	v_and_b32_e32 v175, 0xffff0000, v225
	v_lshlrev_b32_e32 v176, 16, v226
	v_and_b32_e32 v177, 0xffff0000, v226
	v_lshlrev_b32_e32 v178, 16, v227
	v_and_b32_e32 v179, 0xffff0000, v227
	v_mul_f32_e32 v52, v52, v132
	v_mul_f32_e32 v53, v53, v132
	v_mul_f32_e32 v54, v54, v132
	v_mul_f32_e32 v55, v55, v132
	v_mul_f32_e32 v56, v56, v132
	v_mul_f32_e32 v57, v57, v132
	v_mul_f32_e32 v58, v58, v132
	v_mul_f32_e32 v59, v59, v132
	v_fmac_f32_e32 v172, v52, v156
	v_fmac_f32_e32 v173, v53, v157
	v_fmac_f32_e32 v174, v54, v158
	v_fmac_f32_e32 v175, v55, v159
	v_fmac_f32_e32 v176, v56, v160
	v_fmac_f32_e32 v177, v57, v161
	v_fmac_f32_e32 v178, v58, v162
	v_fmac_f32_e32 v179, v59, v163
	v_fmac_f32_e32 v143, v172, v172
	v_fmac_f32_e32 v143, v173, v173
	v_fmac_f32_e32 v143, v174, v174
	v_fmac_f32_e32 v143, v175, v175
	v_fmac_f32_e32 v143, v176, v176
	v_fmac_f32_e32 v143, v177, v177
	v_fmac_f32_e32 v143, v178, v178
	v_fmac_f32_e32 v143, v179, v179
	v_cvt_pk_bf16_f32 v184, v172, v173
	v_cvt_pk_bf16_f32 v185, v174, v175
	v_cvt_pk_bf16_f32 v186, v176, v177
	v_cvt_pk_bf16_f32 v187, v178, v179
	global_store_dwordx4 v140, v[184:187], s[22:23] offset:256
	s_add_u32 s22, s64, 0x48000
	s_addc_u32 s23, s65, 0
	v_lshlrev_b32_e32 v164, 16, v228
	v_and_b32_e32 v165, 0xffff0000, v228
	v_lshlrev_b32_e32 v166, 16, v229
	v_and_b32_e32 v167, 0xffff0000, v229
	v_lshlrev_b32_e32 v168, 16, v230
	v_and_b32_e32 v169, 0xffff0000, v230
	v_lshlrev_b32_e32 v170, 16, v231
	v_and_b32_e32 v171, 0xffff0000, v231
	v_mul_f32_e32 v44, v44, v133
	v_mul_f32_e32 v45, v45, v133
	v_mul_f32_e32 v46, v46, v133
	v_mul_f32_e32 v47, v47, v133
	v_mul_f32_e32 v32, v32, v133
	v_mul_f32_e32 v33, v33, v133
	v_mul_f32_e32 v34, v34, v133
	v_mul_f32_e32 v35, v35, v133
	v_fmac_f32_e32 v164, v44, v148
	v_fmac_f32_e32 v165, v45, v149
	v_fmac_f32_e32 v166, v46, v150
	v_fmac_f32_e32 v167, v47, v151
	v_fmac_f32_e32 v168, v32, v152
	v_fmac_f32_e32 v169, v33, v153
	v_fmac_f32_e32 v170, v34, v154
	v_fmac_f32_e32 v171, v35, v155
	v_mul_f32_e32 v144, v164, v164
	v_fmac_f32_e32 v144, v165, v165
	v_fmac_f32_e32 v144, v166, v166
	v_fmac_f32_e32 v144, v167, v167
	v_fmac_f32_e32 v144, v168, v168
	v_fmac_f32_e32 v144, v169, v169
	v_fmac_f32_e32 v144, v170, v170
	v_fmac_f32_e32 v144, v171, v171
	v_cvt_pk_bf16_f32 v180, v164, v165
	v_cvt_pk_bf16_f32 v181, v166, v167
	v_cvt_pk_bf16_f32 v182, v168, v169
	v_cvt_pk_bf16_f32 v183, v170, v171
	global_store_dwordx4 v140, v[180:183], s[22:23]
	v_lshlrev_b32_e32 v172, 16, v232
	v_and_b32_e32 v173, 0xffff0000, v232
	v_lshlrev_b32_e32 v174, 16, v233
	v_and_b32_e32 v175, 0xffff0000, v233
	v_lshlrev_b32_e32 v176, 16, v234
	v_and_b32_e32 v177, 0xffff0000, v234
	v_lshlrev_b32_e32 v178, 16, v235
	v_and_b32_e32 v179, 0xffff0000, v235
	v_mul_f32_e32 v36, v36, v133
	v_mul_f32_e32 v37, v37, v133
	v_mul_f32_e32 v38, v38, v133
	v_mul_f32_e32 v39, v39, v133
	v_mul_f32_e32 v40, v40, v133
	v_mul_f32_e32 v41, v41, v133
	v_mul_f32_e32 v42, v42, v133
	v_mul_f32_e32 v43, v43, v133
	v_fmac_f32_e32 v172, v36, v156
	v_fmac_f32_e32 v173, v37, v157
	v_fmac_f32_e32 v174, v38, v158
	v_fmac_f32_e32 v175, v39, v159
	v_fmac_f32_e32 v176, v40, v160
	v_fmac_f32_e32 v177, v41, v161
	v_fmac_f32_e32 v178, v42, v162
	v_fmac_f32_e32 v179, v43, v163
	v_fmac_f32_e32 v144, v172, v172
	v_fmac_f32_e32 v144, v173, v173
	v_fmac_f32_e32 v144, v174, v174
	v_fmac_f32_e32 v144, v175, v175
	v_fmac_f32_e32 v144, v176, v176
	v_fmac_f32_e32 v144, v177, v177
	v_fmac_f32_e32 v144, v178, v178
	v_fmac_f32_e32 v144, v179, v179
	v_cvt_pk_bf16_f32 v184, v172, v173
	v_cvt_pk_bf16_f32 v185, v174, v175
	v_cvt_pk_bf16_f32 v186, v176, v177
	v_cvt_pk_bf16_f32 v187, v178, v179
	global_store_dwordx4 v140, v[184:187], s[22:23] offset:256
	s_add_u32 s22, s64, 0x50000
	s_addc_u32 s23, s65, 0
	v_lshlrev_b32_e32 v164, 16, v236
	v_and_b32_e32 v165, 0xffff0000, v236
	v_lshlrev_b32_e32 v166, 16, v237
	v_and_b32_e32 v167, 0xffff0000, v237
	v_lshlrev_b32_e32 v168, 16, v238
	v_and_b32_e32 v169, 0xffff0000, v238
	v_lshlrev_b32_e32 v170, 16, v239
	v_and_b32_e32 v171, 0xffff0000, v239
	v_mul_f32_e32 v28, v28, v134
	v_mul_f32_e32 v29, v29, v134
	v_mul_f32_e32 v30, v30, v134
	v_mul_f32_e32 v31, v31, v134
	v_mul_f32_e32 v16, v16, v134
	v_mul_f32_e32 v17, v17, v134
	v_mul_f32_e32 v18, v18, v134
	v_mul_f32_e32 v19, v19, v134
	v_fmac_f32_e32 v164, v28, v148
	v_fmac_f32_e32 v165, v29, v149
	v_fmac_f32_e32 v166, v30, v150
	v_fmac_f32_e32 v167, v31, v151
	v_fmac_f32_e32 v168, v16, v152
	v_fmac_f32_e32 v169, v17, v153
	v_fmac_f32_e32 v170, v18, v154
	v_fmac_f32_e32 v171, v19, v155
	v_mul_f32_e32 v145, v164, v164
	v_fmac_f32_e32 v145, v165, v165
	v_fmac_f32_e32 v145, v166, v166
	v_fmac_f32_e32 v145, v167, v167
	v_fmac_f32_e32 v145, v168, v168
	v_fmac_f32_e32 v145, v169, v169
	v_fmac_f32_e32 v145, v170, v170
	v_fmac_f32_e32 v145, v171, v171
	v_cvt_pk_bf16_f32 v180, v164, v165
	v_cvt_pk_bf16_f32 v181, v166, v167
	v_cvt_pk_bf16_f32 v182, v168, v169
	v_cvt_pk_bf16_f32 v183, v170, v171
	global_store_dwordx4 v140, v[180:183], s[22:23]
	v_lshlrev_b32_e32 v172, 16, v240
	v_and_b32_e32 v173, 0xffff0000, v240
	v_lshlrev_b32_e32 v174, 16, v241
	v_and_b32_e32 v175, 0xffff0000, v241
	v_lshlrev_b32_e32 v176, 16, v242
	v_and_b32_e32 v177, 0xffff0000, v242
	v_lshlrev_b32_e32 v178, 16, v243
	v_and_b32_e32 v179, 0xffff0000, v243
	v_mul_f32_e32 v20, v20, v134
	v_mul_f32_e32 v21, v21, v134
	v_mul_f32_e32 v22, v22, v134
	v_mul_f32_e32 v23, v23, v134
	v_mul_f32_e32 v24, v24, v134
	v_mul_f32_e32 v25, v25, v134
	v_mul_f32_e32 v26, v26, v134
	v_mul_f32_e32 v27, v27, v134
	v_fmac_f32_e32 v172, v20, v156
	v_fmac_f32_e32 v173, v21, v157
	v_fmac_f32_e32 v174, v22, v158
	v_fmac_f32_e32 v175, v23, v159
	v_fmac_f32_e32 v176, v24, v160
	v_fmac_f32_e32 v177, v25, v161
	v_fmac_f32_e32 v178, v26, v162
	v_fmac_f32_e32 v179, v27, v163
	v_fmac_f32_e32 v145, v172, v172
	v_fmac_f32_e32 v145, v173, v173
	v_fmac_f32_e32 v145, v174, v174
	v_fmac_f32_e32 v145, v175, v175
	v_fmac_f32_e32 v145, v176, v176
	v_fmac_f32_e32 v145, v177, v177
	v_fmac_f32_e32 v145, v178, v178
	v_fmac_f32_e32 v145, v179, v179
	v_cvt_pk_bf16_f32 v184, v172, v173
	v_cvt_pk_bf16_f32 v185, v174, v175
	v_cvt_pk_bf16_f32 v186, v176, v177
	v_cvt_pk_bf16_f32 v187, v178, v179
	global_store_dwordx4 v140, v[184:187], s[22:23] offset:256
	s_add_u32 s22, s64, 0x58000
	s_addc_u32 s23, s65, 0
	v_lshlrev_b32_e32 v164, 16, v244
	v_and_b32_e32 v165, 0xffff0000, v244
	v_lshlrev_b32_e32 v166, 16, v245
	v_and_b32_e32 v167, 0xffff0000, v245
	v_lshlrev_b32_e32 v168, 16, v246
	v_and_b32_e32 v169, 0xffff0000, v246
	v_lshlrev_b32_e32 v170, 16, v247
	v_and_b32_e32 v171, 0xffff0000, v247
	v_mul_f32_e32 v12, v12, v135
	v_mul_f32_e32 v13, v13, v135
	v_mul_f32_e32 v14, v14, v135
	v_mul_f32_e32 v15, v15, v135
	v_mul_f32_e32 v0, v0, v135
	v_mul_f32_e32 v1, v1, v135
	v_mul_f32_e32 v2, v2, v135
	v_mul_f32_e32 v3, v3, v135
	v_fmac_f32_e32 v164, v12, v148
	v_fmac_f32_e32 v165, v13, v149
	v_fmac_f32_e32 v166, v14, v150
	v_fmac_f32_e32 v167, v15, v151
	v_fmac_f32_e32 v168, v0, v152
	v_fmac_f32_e32 v169, v1, v153
	v_fmac_f32_e32 v170, v2, v154
	v_fmac_f32_e32 v171, v3, v155
	v_mul_f32_e32 v146, v164, v164
	v_fmac_f32_e32 v146, v165, v165
	v_fmac_f32_e32 v146, v166, v166
	v_fmac_f32_e32 v146, v167, v167
	v_fmac_f32_e32 v146, v168, v168
	v_fmac_f32_e32 v146, v169, v169
	v_fmac_f32_e32 v146, v170, v170
	v_fmac_f32_e32 v146, v171, v171
	v_cvt_pk_bf16_f32 v180, v164, v165
	v_cvt_pk_bf16_f32 v181, v166, v167
	v_cvt_pk_bf16_f32 v182, v168, v169
	v_cvt_pk_bf16_f32 v183, v170, v171
	global_store_dwordx4 v140, v[180:183], s[22:23]
	v_lshlrev_b32_e32 v172, 16, v248
	v_and_b32_e32 v173, 0xffff0000, v248
	v_lshlrev_b32_e32 v174, 16, v249
	v_and_b32_e32 v175, 0xffff0000, v249
	v_lshlrev_b32_e32 v176, 16, v250
	v_and_b32_e32 v177, 0xffff0000, v250
	v_lshlrev_b32_e32 v178, 16, v251
	v_and_b32_e32 v179, 0xffff0000, v251
	v_mul_f32_e32 v4, v4, v135
	v_mul_f32_e32 v5, v5, v135
	v_mul_f32_e32 v6, v6, v135
	v_mul_f32_e32 v7, v7, v135
	v_mul_f32_e32 v8, v8, v135
	v_mul_f32_e32 v9, v9, v135
	v_mul_f32_e32 v10, v10, v135
	v_mul_f32_e32 v11, v11, v135
	v_fmac_f32_e32 v172, v4, v156
	v_fmac_f32_e32 v173, v5, v157
	v_fmac_f32_e32 v174, v6, v158
	v_fmac_f32_e32 v175, v7, v159
	v_fmac_f32_e32 v176, v8, v160
	v_fmac_f32_e32 v177, v9, v161
	v_fmac_f32_e32 v178, v10, v162
	v_fmac_f32_e32 v179, v11, v163
	v_fmac_f32_e32 v146, v172, v172
	v_fmac_f32_e32 v146, v173, v173
	v_fmac_f32_e32 v146, v174, v174
	v_fmac_f32_e32 v146, v175, v175
	v_fmac_f32_e32 v146, v176, v176
	v_fmac_f32_e32 v146, v177, v177
	v_fmac_f32_e32 v146, v178, v178
	v_fmac_f32_e32 v146, v179, v179
	v_cvt_pk_bf16_f32 v184, v172, v173
	v_cvt_pk_bf16_f32 v185, v174, v175
	v_cvt_pk_bf16_f32 v186, v176, v177
	v_cvt_pk_bf16_f32 v187, v178, v179
	global_store_dwordx4 v140, v[184:187], s[22:23] offset:256
	v_mov_b32_e32 v148, v138
	v_mov_b32_e32 v149, v139
	v_mov_b32_e32 v150, v141
	v_mov_b32_e32 v151, v142
	v_mov_b32_e32 v152, v143
	v_mov_b32_e32 v153, v144
	v_mov_b32_e32 v154, v145
	v_mov_b32_e32 v155, v146
	v_xor_b32_e32 v138, 16, v137
	v_xor_b32_e32 v139, 32, v137
	v_lshlrev_b32_e32 v138, 2, v138
	v_lshlrev_b32_e32 v139, 2, v139
	ds_bpermute_b32 v164, v138, v148
	ds_bpermute_b32 v165, v138, v149
	ds_bpermute_b32 v166, v138, v150
	ds_bpermute_b32 v167, v138, v151
	ds_bpermute_b32 v168, v138, v152
	ds_bpermute_b32 v169, v138, v153
	ds_bpermute_b32 v170, v138, v154
	ds_bpermute_b32 v171, v138, v155
	s_waitcnt lgkmcnt(0)
	v_add_f32_e32 v148, v148, v164
	v_add_f32_e32 v149, v149, v165
	v_add_f32_e32 v150, v150, v166
	v_add_f32_e32 v151, v151, v167
	v_add_f32_e32 v152, v152, v168
	v_add_f32_e32 v153, v153, v169
	v_add_f32_e32 v154, v154, v170
	v_add_f32_e32 v155, v155, v171
	ds_bpermute_b32 v164, v139, v148
	ds_bpermute_b32 v165, v139, v149
	ds_bpermute_b32 v166, v139, v150
	ds_bpermute_b32 v167, v139, v151
	ds_bpermute_b32 v168, v139, v152
	ds_bpermute_b32 v169, v139, v153
	ds_bpermute_b32 v170, v139, v154
	ds_bpermute_b32 v171, v139, v155
	s_waitcnt lgkmcnt(0)
	v_add_f32_e32 v148, v148, v164
	v_add_f32_e32 v149, v149, v165
	v_add_f32_e32 v150, v150, v166
	v_add_f32_e32 v151, v151, v167
	v_add_f32_e32 v152, v152, v168
	v_add_f32_e32 v153, v153, v169
	v_add_f32_e32 v154, v154, v170
	v_add_f32_e32 v155, v155, v171
	s_and_b32 s98, s2, 7
	s_lshl_b32 s98, s98, 3
	s_bfe_u32 s99, s2, 0x30003
	s_or_b32 s98, s98, s99
	s_lshr_b32 s99, s2, 6
	s_mul_i32 s99, s99, 0x42000
	s_lshl_b32 s98, s98, 10
	s_add_u32 s100, s62, s99
	s_addc_u32 s101, s63, 0
	s_add_u32 s100, s100, s98
	s_addc_u32 s101, s101, 0
	v_lshrrev_b32_e32 v158, 8, v136
	v_bfe_u32 v159, v136, 6, 2
	v_and_b32_e32 v160, 15, v136
	v_lshl_add_u32 v160, v158, 6, v160
	v_mul_u32_u24_e32 v159, 0x4200, v159
	v_add_u32_e32 v160, v160, v159
	v_lshlrev_b32_e32 v160, 2, v160
	v_bfe_u32 v161, v136, 4, 2
	v_cmp_eq_u32_e32 vcc, 0, v161
	s_and_saveexec_b64 s[0:1], vcc
	global_store_dword v160, v148, s[100:101]
	global_store_dword v160, v149, s[100:101] offset:64
	global_store_dword v160, v150, s[100:101] offset:128
	global_store_dword v160, v151, s[100:101] offset:192
	global_store_dword v160, v152, s[100:101] offset:512
	global_store_dword v160, v153, s[100:101] offset:576
	global_store_dword v160, v154, s[100:101] offset:640
	global_store_dword v160, v155, s[100:101] offset:704
	s_or_b64 exec, exec, s[0:1]
	v_bfe_u32 v183, v136, 1, 2
	v_lshrrev_b32_e32 v187, 6, v136
	v_lshlrev_b32_e32 v190, 11, v136
	v_lshrrev_b32_e32 v252, 1, v136
	v_and_b32_e32 v132, 48, v136
	v_and_b32_e32 v189, 63, v136
	v_lshrrev_b32_e32 v182, 3, v136
	v_lshlrev_b32_e32 v188, 2, v136
	v_lshl_add_u32 v186, v183, 6, 0
	v_and_b32_e32 v191, 15, v136
	v_cndmask_b32_e64 v1, 0, 1, s[8:9]
	v_mov_b32_e32 v0, v136
	v_cmp_ne_u32_e64 s[6:7], 1, v1
	s_andn2_b64 vcc, exec, s[8:9]
	s_cbranch_vccnz .LBB0_1254
	v_and_b32_e32 v4, 63, v0
	v_ashrrev_i32_e32 v0, 5, v0
	v_readlane_b32 s8, v253, 3
	v_and_b32_e32 v5, -2, v0
	v_lshlrev_b32_e32 v0, 4, v4
	v_mov_b32_e32 v1, 0
	v_readlane_b32 s9, v253, 4
	s_mov_b64 s[0:1], 0x3000
	v_readlane_b32 s12, v253, 7
	v_lshl_add_u64 v[2:3], s[8:9], 0, v[0:1]
	v_lshl_add_u64 v[16:17], v[2:3], 0, s[0:1]
	v_and_b32_e32 v2, 64, v137
	v_add_u32_e32 v2, 64, v2
	v_xor_b32_e32 v3, 32, v137
	v_cmp_lt_i32_e64 s[0:1], v3, v2
	v_mul_u32_u24_e32 v0, 0x4200, v4
	v_lshlrev_b32_e32 v0, 2, v0
	v_cndmask_b32_e64 v3, v137, v3, s[0:1]
	v_lshlrev_b32_e32 v50, 2, v3
	v_xor_b32_e32 v3, 16, v137
	v_cmp_lt_i32_e64 s[0:1], v3, v2
	v_readlane_b32 s13, v253, 8
	v_lshl_add_u64 v[18:19], s[44:45], 0, v[0:1]
	v_cndmask_b32_e64 v3, v137, v3, s[0:1]
	v_lshlrev_b32_e32 v51, 2, v3
	v_xor_b32_e32 v3, 8, v137
	v_cmp_lt_i32_e64 s[0:1], v3, v2
	v_lshlrev_b32_e32 v0, 3, v4
	v_cmp_gt_u32_e32 vcc, 16, v4
	v_cndmask_b32_e64 v3, v137, v3, s[0:1]
	v_lshlrev_b32_e32 v52, 2, v3
	v_xor_b32_e32 v3, 4, v137
	v_cmp_lt_i32_e64 s[0:1], v3, v2
	v_lshl_add_u64 v[20:21], s[64:65], 0, v[0:1]
	v_lshl_add_u64 v[22:23], s[60:61], 0, v[0:1]
	v_cndmask_b32_e64 v3, v137, v3, s[0:1]
	v_lshlrev_b32_e32 v53, 2, v3
	v_xor_b32_e32 v3, 2, v137
	v_cmp_lt_i32_e64 s[0:1], v3, v2
	v_lshl_add_u64 v[24:25], s[58:59], 0, v[0:1]
	v_lshl_add_u32 v26, s2, 4, v5
	v_cndmask_b32_e64 v3, v137, v3, s[0:1]
	v_lshlrev_b32_e32 v54, 2, v3
	v_xor_b32_e32 v3, 1, v137
	v_cmp_lt_i32_e64 s[0:1], v3, v2
	s_lshl_b32 s3, s38, 4
	v_mov_b32_e32 v56, 0x358637bd
	v_cndmask_b32_e64 v2, v137, v3, s[0:1]
	v_lshlrev_b32_e32 v55, 2, v2
	v_cmp_eq_u32_e64 s[0:1], 0, v4
	s_mov_b32 s12, 0x800000
	s_mov_b32 s13, s2
	v_readlane_b32 s10, v253, 5
	v_readlane_b32 s11, v253, 6
	v_readlane_b32 s14, v253, 9
	v_readlane_b32 s15, v253, 10
	v_readlane_b32 s16, v253, 11
	v_readlane_b32 s17, v253, 12
	v_readlane_b32 s18, v253, 13
	v_readlane_b32 s19, v253, 14
	v_readlane_b32 s20, v253, 15
	v_readlane_b32 s21, v253, 16
	v_readlane_b32 s22, v253, 17
	v_readlane_b32 s23, v253, 18
	s_addk_i32 s13, 0x400
	v_add_u32_e32 v26, 0x4000, v26
	s_cmpk_lt_i32 s13, 0x420
	s_cbranch_scc0 .LBB0_1254
	s_branch .LBB0_1246

.LBB0_1303:
	s_or_b64 exec, exec, s[10:11]
	s_mov_b64 s[10:11], exec
	v_mbcnt_lo_u32_b32 v0, s10, 0
	v_mbcnt_hi_u32_b32 v0, s11, v0
	v_cmp_eq_u32_e32 vcc, 0, v0
	s_and_saveexec_b64 s[12:13], vcc
	s_cbranch_execz .LBB0_1305
	s_bcnt1_i32_b64 s3, s[10:11]
	v_mov_b32_e32 v0, 0x2000
	v_mov_b32_e32 v1, s3
	global_atomic_add v0, v1, s[8:9] offset:1024
.LBB0_1305:
	s_or_b64 exec, exec, s[12:13]
.LBB0_1306:
	s_or_b64 exec, exec, s[0:1]
	s_mov_b32 s3, 0
	s_mov_b64 s[20:21], 0
	v_mov_b32_e32 v129, 0
	s_mov_b64 s[0:1], 0x80
	s_mov_b64 s[8:9], 0x40080
	s_mov_b64 s[10:11], 0x100
	s_mov_b64 s[12:13], 0x40100
	s_mov_b64 s[14:15], 0x180
	s_mov_b64 s[16:17], 0x40180
	s_movk_i32 s36, 0x1600
	v_mov_b32_e32 v133, 1
	s_mov_b32 s37, s96
	s_waitcnt lgkmcnt(0)
	s_barrier
	s_and_b32 s24, s2, 7
	s_lshl_b32 s24, s24, 5
	s_lshr_b32 s25, s2, 3
	s_add_u32 s24, s24, s25
	s_add_u32 s98, s24, 0x0
	s_mul_hi_u32 s99, s98, 0x2e8ba2f
	s_mul_i32 s100, s99, 0x58
	s_sub_u32 s100, s98, s100
	s_lshl_b32 s99, s99, 2
	s_and_b32 s100, s100, 3
	s_add_u32 s26, s99, s100
	s_add_u32 s98, s24, 0x100
	s_mul_hi_u32 s99, s98, 0x2e8ba2f
	s_mul_i32 s100, s99, 0x58
	s_sub_u32 s100, s98, s100
	s_lshl_b32 s99, s99, 2
	s_and_b32 s100, s100, 3
	s_add_u32 s27, s99, s100
	s_cmpk_lt_u32 s98, 0x5ac
	s_cselect_b32 s27, s27, s26
	s_cmpk_lt_u32 s99, 0x40
	s_cselect_b32 s27, s27, s26
	s_add_u32 s98, s24, 0x200
	s_mul_hi_u32 s99, s98, 0x2e8ba2f
	s_mul_i32 s100, s99, 0x58
	s_sub_u32 s100, s98, s100
	s_lshl_b32 s99, s99, 2
	s_and_b32 s100, s100, 3
	s_add_u32 s28, s99, s100
	s_cmpk_lt_u32 s98, 0x5ac
	s_cselect_b32 s28, s28, s26
	s_cmpk_lt_u32 s99, 0x40
	s_cselect_b32 s28, s28, s26
	s_add_u32 s98, s24, 0x300
	s_mul_hi_u32 s99, s98, 0x2e8ba2f
	s_mul_i32 s100, s99, 0x58
	s_sub_u32 s100, s98, s100
	s_lshl_b32 s99, s99, 2
	s_and_b32 s100, s100, 3
	s_add_u32 s29, s99, s100
	s_cmpk_lt_u32 s98, 0x5ac
	s_cselect_b32 s29, s29, s26
	s_cmpk_lt_u32 s99, 0x40
	s_cselect_b32 s29, s29, s26
	s_add_u32 s98, s24, 0x400
	s_mul_hi_u32 s99, s98, 0x2e8ba2f
	s_mul_i32 s100, s99, 0x58
	s_sub_u32 s100, s98, s100
	s_lshl_b32 s99, s99, 2
	s_and_b32 s100, s100, 3
	s_add_u32 s30, s99, s100
	s_cmpk_lt_u32 s98, 0x5ac
	s_cselect_b32 s30, s30, s26
	s_cmpk_lt_u32 s99, 0x40
	s_cselect_b32 s30, s30, s26
	s_add_u32 s98, s24, 0x500
	s_mul_hi_u32 s99, s98, 0x2e8ba2f
	s_mul_i32 s100, s99, 0x58
	s_sub_u32 s100, s98, s100
	s_lshl_b32 s99, s99, 2
	s_and_b32 s100, s100, 3
	s_add_u32 s31, s99, s100
	s_cmpk_lt_u32 s98, 0x5ac
	s_cselect_b32 s31, s31, s26
	s_cmpk_lt_u32 s99, 0x40
	s_cselect_b32 s31, s31, s26
	v_and_b32_e32 v140, 0xff, v136
	v_lshrrev_b32_e32 v141, 8, v136
	v_mul_u32_u24_e32 v141, 0x84000, v141
	v_lshl_add_u32 v140, v140, 2, v141
	v_lshlrev_b32_e32 v141, 2, v136
	s_lshl_b32 s98, s26, 10
	s_add_u32 s18, s62, s98
	s_addc_u32 s19, s63, 0
	global_load_dword v192, v140, s[18:19]
	s_add_u32 s18, s18, 0x10800
	s_addc_u32 s19, s19, 0
	global_load_dword v193, v140, s[18:19]
	s_add_u32 s18, s18, 0x10800
	s_addc_u32 s19, s19, 0
	global_load_dword v194, v140, s[18:19]
	s_add_u32 s18, s18, 0x10800
	s_addc_u32 s19, s19, 0
	global_load_dword v195, v140, s[18:19]
	s_add_u32 s18, s18, 0x10800
	s_addc_u32 s19, s19, 0
	global_load_dword v196, v140, s[18:19]
	s_add_u32 s18, s18, 0x10800
	s_addc_u32 s19, s19, 0
	global_load_dword v197, v140, s[18:19]
	s_add_u32 s18, s18, 0x10800
	s_addc_u32 s19, s19, 0
	global_load_dword v198, v140, s[18:19]
	s_add_u32 s18, s18, 0x10800
	s_addc_u32 s19, s19, 0
	global_load_dword v199, v140, s[18:19]
	s_lshl_b32 s98, s27, 10
	s_add_u32 s18, s62, s98
	s_addc_u32 s19, s63, 0
	global_load_dword v200, v140, s[18:19]
	s_add_u32 s18, s18, 0x10800
	s_addc_u32 s19, s19, 0
	global_load_dword v201, v140, s[18:19]
	s_add_u32 s18, s18, 0x10800
	s_addc_u32 s19, s19, 0
	global_load_dword v202, v140, s[18:19]
	s_add_u32 s18, s18, 0x10800
	s_addc_u32 s19, s19, 0
	global_load_dword v203, v140, s[18:19]
	s_add_u32 s18, s18, 0x10800
	s_addc_u32 s19, s19, 0
	global_load_dword v204, v140, s[18:19]
	s_add_u32 s18, s18, 0x10800
	s_addc_u32 s19, s19, 0
	global_load_dword v205, v140, s[18:19]
	s_add_u32 s18, s18, 0x10800
	s_addc_u32 s19, s19, 0
	global_load_dword v206, v140, s[18:19]
	s_add_u32 s18, s18, 0x10800
	s_addc_u32 s19, s19, 0
	global_load_dword v207, v140, s[18:19]
	s_lshl_b32 s98, s28, 10
	s_add_u32 s18, s62, s98
	s_addc_u32 s19, s63, 0
	global_load_dword v208, v140, s[18:19]
	s_add_u32 s18, s18, 0x10800
	s_addc_u32 s19, s19, 0
	global_load_dword v209, v140, s[18:19]
	s_add_u32 s18, s18, 0x10800
	s_addc_u32 s19, s19, 0
	global_load_dword v210, v140, s[18:19]
	s_add_u32 s18, s18, 0x10800
	s_addc_u32 s19, s19, 0
	global_load_dword v211, v140, s[18:19]
	s_add_u32 s18, s18, 0x10800
	s_addc_u32 s19, s19, 0
	global_load_dword v212, v140, s[18:19]
	s_add_u32 s18, s18, 0x10800
	s_addc_u32 s19, s19, 0
	global_load_dword v213, v140, s[18:19]
	s_add_u32 s18, s18, 0x10800
	s_addc_u32 s19, s19, 0
	global_load_dword v214, v140, s[18:19]
	s_add_u32 s18, s18, 0x10800
	s_addc_u32 s19, s19, 0
	global_load_dword v215, v140, s[18:19]
	s_lshl_b32 s98, s29, 10
	s_add_u32 s18, s62, s98
	s_addc_u32 s19, s63, 0
	global_load_dword v216, v140, s[18:19]
	s_add_u32 s18, s18, 0x10800
	s_addc_u32 s19, s19, 0
	global_load_dword v217, v140, s[18:19]
	s_add_u32 s18, s18, 0x10800
	s_addc_u32 s19, s19, 0
	global_load_dword v218, v140, s[18:19]
	s_add_u32 s18, s18, 0x10800
	s_addc_u32 s19, s19, 0
	global_load_dword v219, v140, s[18:19]
	s_add_u32 s18, s18, 0x10800
	s_addc_u32 s19, s19, 0
	global_load_dword v220, v140, s[18:19]
	s_add_u32 s18, s18, 0x10800
	s_addc_u32 s19, s19, 0
	global_load_dword v221, v140, s[18:19]
	s_add_u32 s18, s18, 0x10800
	s_addc_u32 s19, s19, 0
	global_load_dword v222, v140, s[18:19]
	s_add_u32 s18, s18, 0x10800
	s_addc_u32 s19, s19, 0
	global_load_dword v223, v140, s[18:19]
	s_lshl_b32 s98, s30, 10
	s_add_u32 s18, s62, s98
	s_addc_u32 s19, s63, 0
	global_load_dword v224, v140, s[18:19]
	s_add_u32 s18, s18, 0x10800
	s_addc_u32 s19, s19, 0
	global_load_dword v225, v140, s[18:19]
	s_add_u32 s18, s18, 0x10800
	s_addc_u32 s19, s19, 0
	global_load_dword v226, v140, s[18:19]
	s_add_u32 s18, s18, 0x10800
	s_addc_u32 s19, s19, 0
	global_load_dword v227, v140, s[18:19]
	s_add_u32 s18, s18, 0x10800
	s_addc_u32 s19, s19, 0
	global_load_dword v228, v140, s[18:19]
	s_add_u32 s18, s18, 0x10800
	s_addc_u32 s19, s19, 0
	global_load_dword v229, v140, s[18:19]
	s_add_u32 s18, s18, 0x10800
	s_addc_u32 s19, s19, 0
	global_load_dword v230, v140, s[18:19]
	s_add_u32 s18, s18, 0x10800
	s_addc_u32 s19, s19, 0
	global_load_dword v231, v140, s[18:19]
	s_lshl_b32 s98, s31, 10
	s_add_u32 s18, s62, s98
	s_addc_u32 s19, s63, 0
	global_load_dword v232, v140, s[18:19]
	s_add_u32 s18, s18, 0x10800
	s_addc_u32 s19, s19, 0
	global_load_dword v233, v140, s[18:19]
	s_add_u32 s18, s18, 0x10800
	s_addc_u32 s19, s19, 0
	global_load_dword v234, v140, s[18:19]
	s_add_u32 s18, s18, 0x10800
	s_addc_u32 s19, s19, 0
	global_load_dword v235, v140, s[18:19]
	s_add_u32 s18, s18, 0x10800
	s_addc_u32 s19, s19, 0
	global_load_dword v236, v140, s[18:19]
	s_add_u32 s18, s18, 0x10800
	s_addc_u32 s19, s19, 0
	global_load_dword v237, v140, s[18:19]
	s_add_u32 s18, s18, 0x10800
	s_addc_u32 s19, s19, 0
	global_load_dword v238, v140, s[18:19]
	s_add_u32 s18, s18, 0x10800
	s_addc_u32 s19, s19, 0
	global_load_dword v239, v140, s[18:19]
	s_waitcnt vmcnt(0)
	v_add_f32_e32 v192, v192, v193
	v_add_f32_e32 v192, v192, v194
	v_add_f32_e32 v192, v192, v195
	v_add_f32_e32 v192, v192, v196
	v_add_f32_e32 v192, v192, v197
	v_add_f32_e32 v192, v192, v198
	v_add_f32_e32 v192, v192, v199
	ds_write_b32 v141, v192 offset:32768
	v_add_f32_e32 v200, v200, v201
	v_add_f32_e32 v200, v200, v202
	v_add_f32_e32 v200, v200, v203
	v_add_f32_e32 v200, v200, v204
	v_add_f32_e32 v200, v200, v205
	v_add_f32_e32 v200, v200, v206
	v_add_f32_e32 v200, v200, v207
	ds_write_b32 v141, v200 offset:34816
	v_add_f32_e32 v208, v208, v209
	v_add_f32_e32 v208, v208, v210
	v_add_f32_e32 v208, v208, v211
	v_add_f32_e32 v208, v208, v212
	v_add_f32_e32 v208, v208, v213
	v_add_f32_e32 v208, v208, v214
	v_add_f32_e32 v208, v208, v215
	ds_write_b32 v141, v208 offset:36864
	v_add_f32_e32 v216, v216, v217
	v_add_f32_e32 v216, v216, v218
	v_add_f32_e32 v216, v216, v219
	v_add_f32_e32 v216, v216, v220
	v_add_f32_e32 v216, v216, v221
	v_add_f32_e32 v216, v216, v222
	v_add_f32_e32 v216, v216, v223
	ds_write_b32 v141, v216 offset:38912
	v_add_f32_e32 v224, v224, v225
	v_add_f32_e32 v224, v224, v226
	v_add_f32_e32 v224, v224, v227
	v_add_f32_e32 v224, v224, v228
	v_add_f32_e32 v224, v224, v229
	v_add_f32_e32 v224, v224, v230
	v_add_f32_e32 v224, v224, v231
	ds_write_b32 v141, v224 offset:40960
	v_add_f32_e32 v232, v232, v233
	v_add_f32_e32 v232, v232, v234
	v_add_f32_e32 v232, v232, v235
	v_add_f32_e32 v232, v232, v236
	v_add_f32_e32 v232, v232, v237
	v_add_f32_e32 v232, v232, v238
	v_add_f32_e32 v232, v232, v239
	ds_write_b32 v141, v232 offset:43008
	s_waitcnt lgkmcnt(0)
	s_barrier
	v_cmp_gt_u32_e32 vcc, 0x100, v136
	s_and_saveexec_b64 s[18:19], vcc
	ds_read_b32 v192, v141 offset:32768
	ds_read_b32 v193, v141 offset:33792
	ds_read_b32 v194, v141 offset:34816
	ds_read_b32 v195, v141 offset:35840
	ds_read_b32 v196, v141 offset:36864
	ds_read_b32 v197, v141 offset:37888
	ds_read_b32 v198, v141 offset:38912
	ds_read_b32 v199, v141 offset:39936
	ds_read_b32 v200, v141 offset:40960
	ds_read_b32 v201, v141 offset:41984
	ds_read_b32 v202, v141 offset:43008
	ds_read_b32 v203, v141 offset:44032
	s_mov_b32 s25, 0x3a800000
	v_mov_b32_e32 v144, 0x358637bd
	s_waitcnt lgkmcnt(0)
	v_add_f32_e32 v192, v192, v193
	v_add_f32_e32 v194, v194, v195
	v_add_f32_e32 v196, v196, v197
	v_add_f32_e32 v198, v198, v199
	v_add_f32_e32 v200, v200, v201
	v_add_f32_e32 v202, v202, v203
	v_fma_f32 v192, v192, s25, v144
	v_fma_f32 v194, v194, s25, v144
	v_fma_f32 v196, v196, s25, v144
	v_fma_f32 v198, v198, s25, v144
	v_fma_f32 v200, v200, s25, v144
	v_fma_f32 v202, v202, s25, v144
	v_rsq_f32_e32 v192, v192
	v_rsq_f32_e32 v194, v194
	v_rsq_f32_e32 v196, v196
	v_rsq_f32_e32 v198, v198
	v_rsq_f32_e32 v200, v200
	v_rsq_f32_e32 v202, v202
	s_lshl_b32 s98, s26, 10
	s_add_u32 s100, s48, s98
	s_addc_u32 s101, s49, 0
	global_store_dword v141, v192, s[100:101]
	s_lshl_b32 s98, s27, 10
	s_add_u32 s100, s48, s98
	s_addc_u32 s101, s49, 0
	global_store_dword v141, v194, s[100:101]
	s_lshl_b32 s98, s28, 10
	s_add_u32 s100, s48, s98
	s_addc_u32 s101, s49, 0
	global_store_dword v141, v196, s[100:101]
	s_lshl_b32 s98, s29, 10
	s_add_u32 s100, s48, s98
	s_addc_u32 s101, s49, 0
	global_store_dword v141, v198, s[100:101]
	s_lshl_b32 s98, s30, 10
	s_add_u32 s100, s48, s98
	s_addc_u32 s101, s49, 0
	global_store_dword v141, v200, s[100:101]
	s_lshl_b32 s98, s31, 10
	s_add_u32 s100, s48, s98
	s_addc_u32 s101, s49, 0
	global_store_dword v141, v202, s[100:101]
	s_or_b64 exec, exec, s[18:19]
	s_waitcnt vmcnt(0)
	s_barrier
	s_branch .LBB0_1310

.LBB0_1383:
	s_or_b64 exec, exec, s[12:13]
.LBB0_1384:
	s_or_b64 exec, exec, s[0:1]
	s_and_b64 vcc, exec, s[4:5]
	s_waitcnt lgkmcnt(0)
	s_barrier
	s_cbranch_vccnz .LBB0_1390
	v_readlane_b32 s8, v254, 4
	v_mul_u32_u24_e32 v0, 0x1600, v191
	v_mov_b32_e32 v1, 0
	v_readlane_b32 s12, v254, 8
	v_readlane_b32 s13, v254, 9
	v_mov_b32_e32 v133, v1
	v_mul_u32_u24_e32 v6, 0x160, v187
	v_lshl_add_u64 v[2:3], s[12:13], 0, v[0:1]
	v_lshl_add_u64 v[4:5], v[2:3], 0, v[132:133]
	v_lshl_add_u64 v[2:3], s[66:67], 0, v[0:1]
	v_and_b32_e32 v7, 4, v188
	v_lshl_add_u64 v[2:3], v[2:3], 0, v[132:133]
	v_lshlrev_b32_e32 v0, 1, v6
	v_and_or_b32 v8, v182, 16, v7
	v_readlane_b32 s9, v254, 5
	v_lshl_add_u64 v[2:3], v[2:3], 0, v[0:1]
	v_lshl_add_u64 v[4:5], v[4:5], 0, v[0:1]
	v_lshlrev_b32_e32 v0, 13, v187
	v_lshl_add_u32 v6, v189, 2, 0
	s_movk_i32 s0, 0x100
	v_and_b32_e32 v9, 60, v252
	v_lshlrev_b32_e32 v8, 8, v8
	v_lshl_or_b32 v17, v183, 3, v7
	v_and_b32_e32 v7, 7, v136
	s_mov_b32 s9, 0
	v_cmp_gt_u32_e64 s[0:1], s0, v136
	v_add3_u32 v16, v186, v9, v8
	v_cmp_eq_u32_e64 s[4:5], 0, v7
	s_lshl_b32 s3, s2, 5
	s_lshl_b32 s12, s38, 5
	v_mov_b32_e32 v18, 0x1600
	v_add_u32_e32 v19, v6, v0
	s_mov_b32 s13, s2
	v_readlane_b32 s10, v254, 6
	v_readlane_b32 s11, v254, 7
	v_readlane_b32 s14, v254, 10
	v_readlane_b32 s15, v254, 11
	v_readlane_b32 s16, v254, 12
	v_readlane_b32 s17, v254, 13
	v_readlane_b32 s18, v254, 14
	v_readlane_b32 s19, v254, 15
	v_readlane_b32 s20, v254, 16
	v_readlane_b32 s21, v254, 17
	v_readlane_b32 s22, v254, 18
	v_readlane_b32 s23, v254, 19
	s_branch .LBB0_1387

.LBB0_1465:
	s_or_b64 exec, exec, s[8:9]
	s_mov_b64 s[8:9], exec
	v_mbcnt_lo_u32_b32 v140, s8, 0
	v_mbcnt_hi_u32_b32 v140, s9, v140
	v_cmp_eq_u32_e32 vcc, 0, v140
	s_and_saveexec_b64 s[10:11], vcc
	s_cbranch_execz .LBB0_1467
	s_bcnt1_i32_b64 s3, s[8:9]
	v_mov_b32_e32 v140, 0x2000
	v_mov_b32_e32 v141, s3
	global_atomic_add v140, v141, s[4:5] offset:1024
.LBB0_1467:
	s_or_b64 exec, exec, s[10:11]
.LBB0_1468:
	s_or_b64 exec, exec, s[0:1]
	s_and_b64 vcc, exec, s[6:7]
	s_waitcnt lgkmcnt(0)
	s_barrier
	s_and_b32 s99, s2, 7
	s_lshl_b32 s99, s99, 3
	s_bfe_u32 s100, s2, 0x30003
	s_or_b32 s99, s99, s100
	s_lshr_b32 s100, s2, 6
	v_and_b32_e32 v172, 0xff, v136
	v_lshrrev_b32_e32 v173, 8, v136
	v_mul_u32_u24_e32 v173, 0x84000, v173
	v_lshl_add_u32 v172, v172, 2, v173
	s_lshl_b32 s24, s99, 10
	s_add_u32 s18, s44, s24
	s_addc_u32 s19, s45, 0
	global_load_dword v164, v172, s[18:19]
	s_add_u32 s18, s18, 0x10800
	s_addc_u32 s19, s19, 0
	global_load_dword v165, v172, s[18:19]
	s_add_u32 s18, s18, 0x10800
	s_addc_u32 s19, s19, 0
	global_load_dword v166, v172, s[18:19]
	s_add_u32 s18, s18, 0x10800
	s_addc_u32 s19, s19, 0
	global_load_dword v167, v172, s[18:19]
	s_add_u32 s18, s18, 0x10800
	s_addc_u32 s19, s19, 0
	global_load_dword v168, v172, s[18:19]
	s_add_u32 s18, s18, 0x10800
	s_addc_u32 s19, s19, 0
	global_load_dword v169, v172, s[18:19]
	s_add_u32 s18, s18, 0x10800
	s_addc_u32 s19, s19, 0
	global_load_dword v170, v172, s[18:19]
	s_add_u32 s18, s18, 0x10800
	s_addc_u32 s19, s19, 0
	global_load_dword v171, v172, s[18:19]
	v_lshrrev_b32_e32 v141, 8, v136
	v_and_b32_e32 v142, 15, v136
	v_lshl_add_u32 v141, v141, 6, v142
	v_bfe_u32 v144, v136, 6, 2
	v_bfe_u32 v145, v136, 4, 2
	v_lshlrev_b32_e32 v144, 5, v144
	v_lshl_add_u32 v144, v145, 3, v144
	s_lshl_b32 s24, s100, 8
	v_add_u32_e32 v144, s24, v144
	s_lshl_b32 s25, s99, 8
	v_add_u32_e32 v145, s25, v141
	v_lshl_add_u32 v146, v145, 10, v144
	v_lshlrev_b32_e32 v139, 1, v146
	v_lshlrev_b32_e32 v140, 2, v146
	v_lshlrev_b32_e32 v138, 2, v144
	v_readlane_b32 s18, v253, 3
	v_readlane_b32 s19, v253, 4
	v_readlane_b32 s20, v254, 52
	v_readlane_b32 s21, v254, 53
	s_nop 4
	s_add_u32 s18, s18, 0x5000
	s_addc_u32 s19, s19, 0
	global_load_dwordx4 v[148:151], v138, s[18:19]
	global_load_dwordx4 v[152:155], v138, s[18:19] offset:16
	global_load_dwordx4 v[156:159], v138, s[18:19] offset:512
	global_load_dwordx4 v[160:163], v138, s[18:19] offset:528
	s_add_u32 s22, s64, 0x0
	s_addc_u32 s23, s65, 0
	global_load_dwordx4 v[188:191], v139, s[22:23] nt
	global_load_dwordx4 v[192:195], v139, s[22:23] offset:256 nt
	s_add_u32 s22, s64, 0x8000
	s_addc_u32 s23, s65, 0
	global_load_dwordx4 v[196:199], v139, s[22:23] nt
	global_load_dwordx4 v[200:203], v139, s[22:23] offset:256 nt
	s_add_u32 s22, s64, 0x10000
	s_addc_u32 s23, s65, 0
	global_load_dwordx4 v[204:207], v139, s[22:23] nt
	global_load_dwordx4 v[208:211], v139, s[22:23] offset:256 nt
	s_add_u32 s22, s64, 0x18000
	s_addc_u32 s23, s65, 0
	global_load_dwordx4 v[212:215], v139, s[22:23] nt
	global_load_dwordx4 v[216:219], v139, s[22:23] offset:256 nt
	s_add_u32 s22, s64, 0x40000
	s_addc_u32 s23, s65, 0
	global_load_dwordx4 v[220:223], v139, s[22:23] nt
	global_load_dwordx4 v[224:227], v139, s[22:23] offset:256 nt
	s_add_u32 s22, s64, 0x48000
	s_addc_u32 s23, s65, 0
	global_load_dwordx4 v[228:231], v139, s[22:23] nt
	global_load_dwordx4 v[232:235], v139, s[22:23] offset:256 nt
	s_add_u32 s22, s64, 0x50000
	s_addc_u32 s23, s65, 0
	global_load_dwordx4 v[236:239], v139, s[22:23] nt
	global_load_dwordx4 v[240:243], v139, s[22:23] offset:256 nt
	s_add_u32 s22, s64, 0x58000
	s_addc_u32 s23, s65, 0
	global_load_dwordx4 v[244:247], v139, s[22:23] nt
	global_load_dwordx4 v[248:251], v139, s[22:23] offset:256 nt
	s_waitcnt vmcnt(20)
	v_add_f32_e32 v164, v164, v165
	v_add_f32_e32 v164, v164, v166
	v_add_f32_e32 v164, v164, v167
	v_add_f32_e32 v164, v164, v168
	v_add_f32_e32 v164, v164, v169
	v_add_f32_e32 v164, v164, v170
	v_add_f32_e32 v164, v164, v171
	v_lshlrev_b32_e32 v173, 2, v136
	ds_write_b32 v173, v164
	s_waitcnt lgkmcnt(0)
	s_barrier
	v_lshlrev_b32_e32 v142, 2, v141
	ds_read_b32 v128, v142 offset:0
	ds_read_b32 v174, v142 offset:1024
	ds_read_b32 v129, v142 offset:64
	ds_read_b32 v175, v142 offset:1088
	ds_read_b32 v130, v142 offset:128
	ds_read_b32 v176, v142 offset:1152
	ds_read_b32 v131, v142 offset:192
	ds_read_b32 v177, v142 offset:1216
	ds_read_b32 v132, v142 offset:512
	ds_read_b32 v178, v142 offset:1536
	ds_read_b32 v133, v142 offset:576
	ds_read_b32 v179, v142 offset:1600
	ds_read_b32 v134, v142 offset:640
	ds_read_b32 v180, v142 offset:1664
	ds_read_b32 v135, v142 offset:704
	ds_read_b32 v181, v142 offset:1728
	s_waitcnt lgkmcnt(0)
	s_mov_b32 s101, 0x3a800000
	v_mov_b32_e32 v143, 0x358637bd
	v_add_f32_e32 v128, v128, v174
	v_add_f32_e32 v129, v129, v175
	v_add_f32_e32 v130, v130, v176
	v_add_f32_e32 v131, v131, v177
	v_add_f32_e32 v132, v132, v178
	v_add_f32_e32 v133, v133, v179
	v_add_f32_e32 v134, v134, v180
	v_add_f32_e32 v135, v135, v181
	v_fma_f32 v128, v128, s101, v143
	v_fma_f32 v129, v129, s101, v143
	v_fma_f32 v130, v130, s101, v143
	v_fma_f32 v131, v131, s101, v143
	v_fma_f32 v132, v132, s101, v143
	v_fma_f32 v133, v133, s101, v143
	v_fma_f32 v134, v134, s101, v143
	v_fma_f32 v135, v135, s101, v143
	v_rsq_f32_e32 v128, v128
	v_rsq_f32_e32 v129, v129
	v_rsq_f32_e32 v130, v130
	v_rsq_f32_e32 v131, v131
	v_rsq_f32_e32 v132, v132
	v_rsq_f32_e32 v133, v133
	v_rsq_f32_e32 v134, v134
	v_rsq_f32_e32 v135, v135
	s_waitcnt vmcnt(0)
	s_add_u32 s22, s20, 0x0
	s_addc_u32 s23, s21, 0
	v_lshlrev_b32_e32 v164, 16, v188
	v_and_b32_e32 v165, 0xffff0000, v188
	v_lshlrev_b32_e32 v166, 16, v189
	v_and_b32_e32 v167, 0xffff0000, v189
	v_lshlrev_b32_e32 v168, 16, v190
	v_and_b32_e32 v169, 0xffff0000, v190
	v_lshlrev_b32_e32 v170, 16, v191
	v_and_b32_e32 v171, 0xffff0000, v191
	v_mul_f32_e32 v124, v124, v128
	v_mul_f32_e32 v125, v125, v128
	v_mul_f32_e32 v126, v126, v128
	v_mul_f32_e32 v127, v127, v128
	v_mul_f32_e32 v112, v112, v128
	v_mul_f32_e32 v113, v113, v128
	v_mul_f32_e32 v114, v114, v128
	v_mul_f32_e32 v115, v115, v128
	v_fmac_f32_e32 v164, v124, v148
	v_fmac_f32_e32 v165, v125, v149
	v_fmac_f32_e32 v166, v126, v150
	v_fmac_f32_e32 v167, v127, v151
	v_fmac_f32_e32 v168, v112, v152
	v_fmac_f32_e32 v169, v113, v153
	v_fmac_f32_e32 v170, v114, v154
	v_fmac_f32_e32 v171, v115, v155
	global_store_dwordx4 v140, v[164:167], s[22:23]
	global_store_dwordx4 v140, v[168:171], s[22:23] offset:16
	v_lshlrev_b32_e32 v172, 16, v192
	v_and_b32_e32 v173, 0xffff0000, v192
	v_lshlrev_b32_e32 v174, 16, v193
	v_and_b32_e32 v175, 0xffff0000, v193
	v_lshlrev_b32_e32 v176, 16, v194
	v_and_b32_e32 v177, 0xffff0000, v194
	v_lshlrev_b32_e32 v178, 16, v195
	v_and_b32_e32 v179, 0xffff0000, v195
	v_mul_f32_e32 v120, v120, v128
	v_mul_f32_e32 v121, v121, v128
	v_mul_f32_e32 v122, v122, v128
	v_mul_f32_e32 v123, v123, v128
	v_mul_f32_e32 v116, v116, v128
	v_mul_f32_e32 v117, v117, v128
	v_mul_f32_e32 v118, v118, v128
	v_mul_f32_e32 v119, v119, v128
	v_fmac_f32_e32 v172, v120, v156
	v_fmac_f32_e32 v173, v121, v157
	v_fmac_f32_e32 v174, v122, v158
	v_fmac_f32_e32 v175, v123, v159
	v_fmac_f32_e32 v176, v116, v160
	v_fmac_f32_e32 v177, v117, v161
	v_fmac_f32_e32 v178, v118, v162
	v_fmac_f32_e32 v179, v119, v163
	global_store_dwordx4 v140, v[172:175], s[22:23] offset:512
	global_store_dwordx4 v140, v[176:179], s[22:23] offset:528
	s_add_u32 s22, s20, 0x10000
	s_addc_u32 s23, s21, 0
	v_lshlrev_b32_e32 v180, 16, v196
	v_and_b32_e32 v181, 0xffff0000, v196
	v_lshlrev_b32_e32 v182, 16, v197
	v_and_b32_e32 v183, 0xffff0000, v197
	v_lshlrev_b32_e32 v184, 16, v198
	v_and_b32_e32 v185, 0xffff0000, v198
	v_lshlrev_b32_e32 v186, 16, v199
	v_and_b32_e32 v187, 0xffff0000, v199
	v_mul_f32_e32 v108, v108, v129
	v_mul_f32_e32 v109, v109, v129
	v_mul_f32_e32 v110, v110, v129
	v_mul_f32_e32 v111, v111, v129
	v_mul_f32_e32 v96, v96, v129
	v_mul_f32_e32 v97, v97, v129
	v_mul_f32_e32 v98, v98, v129
	v_mul_f32_e32 v99, v99, v129
	v_fmac_f32_e32 v180, v108, v148
	v_fmac_f32_e32 v181, v109, v149
	v_fmac_f32_e32 v182, v110, v150
	v_fmac_f32_e32 v183, v111, v151
	v_fmac_f32_e32 v184, v96, v152
	v_fmac_f32_e32 v185, v97, v153
	v_fmac_f32_e32 v186, v98, v154
	v_fmac_f32_e32 v187, v99, v155
	global_store_dwordx4 v140, v[180:183], s[22:23]
	global_store_dwordx4 v140, v[184:187], s[22:23] offset:16
	v_lshlrev_b32_e32 v164, 16, v200
	v_and_b32_e32 v165, 0xffff0000, v200
	v_lshlrev_b32_e32 v166, 16, v201
	v_and_b32_e32 v167, 0xffff0000, v201
	v_lshlrev_b32_e32 v168, 16, v202
	v_and_b32_e32 v169, 0xffff0000, v202
	v_lshlrev_b32_e32 v170, 16, v203
	v_and_b32_e32 v171, 0xffff0000, v203
	v_mul_f32_e32 v100, v100, v129
	v_mul_f32_e32 v101, v101, v129
	v_mul_f32_e32 v102, v102, v129
	v_mul_f32_e32 v103, v103, v129
	v_mul_f32_e32 v104, v104, v129
	v_mul_f32_e32 v105, v105, v129
	v_mul_f32_e32 v106, v106, v129
	v_mul_f32_e32 v107, v107, v129
	v_fmac_f32_e32 v164, v100, v156
	v_fmac_f32_e32 v165, v101, v157
	v_fmac_f32_e32 v166, v102, v158
	v_fmac_f32_e32 v167, v103, v159
	v_fmac_f32_e32 v168, v104, v160
	v_fmac_f32_e32 v169, v105, v161
	v_fmac_f32_e32 v170, v106, v162
	v_fmac_f32_e32 v171, v107, v163
	global_store_dwordx4 v140, v[164:167], s[22:23] offset:512
	global_store_dwordx4 v140, v[168:171], s[22:23] offset:528
	s_add_u32 s22, s20, 0x20000
	s_addc_u32 s23, s21, 0
	v_lshlrev_b32_e32 v172, 16, v204
	v_and_b32_e32 v173, 0xffff0000, v204
	v_lshlrev_b32_e32 v174, 16, v205
	v_and_b32_e32 v175, 0xffff0000, v205
	v_lshlrev_b32_e32 v176, 16, v206
	v_and_b32_e32 v177, 0xffff0000, v206
	v_lshlrev_b32_e32 v178, 16, v207
	v_and_b32_e32 v179, 0xffff0000, v207
	v_mul_f32_e32 v92, v92, v130
	v_mul_f32_e32 v93, v93, v130
	v_mul_f32_e32 v94, v94, v130
	v_mul_f32_e32 v95, v95, v130
	v_mul_f32_e32 v80, v80, v130
	v_mul_f32_e32 v81, v81, v130
	v_mul_f32_e32 v82, v82, v130
	v_mul_f32_e32 v83, v83, v130
	v_fmac_f32_e32 v172, v92, v148
	v_fmac_f32_e32 v173, v93, v149
	v_fmac_f32_e32 v174, v94, v150
	v_fmac_f32_e32 v175, v95, v151
	v_fmac_f32_e32 v176, v80, v152
	v_fmac_f32_e32 v177, v81, v153
	v_fmac_f32_e32 v178, v82, v154
	v_fmac_f32_e32 v179, v83, v155
	global_store_dwordx4 v140, v[172:175], s[22:23]
	global_store_dwordx4 v140, v[176:179], s[22:23] offset:16
	v_lshlrev_b32_e32 v180, 16, v208
	v_and_b32_e32 v181, 0xffff0000, v208
	v_lshlrev_b32_e32 v182, 16, v209
	v_and_b32_e32 v183, 0xffff0000, v209
	v_lshlrev_b32_e32 v184, 16, v210
	v_and_b32_e32 v185, 0xffff0000, v210
	v_lshlrev_b32_e32 v186, 16, v211
	v_and_b32_e32 v187, 0xffff0000, v211
	v_mul_f32_e32 v84, v84, v130
	v_mul_f32_e32 v85, v85, v130
	v_mul_f32_e32 v86, v86, v130
	v_mul_f32_e32 v87, v87, v130
	v_mul_f32_e32 v88, v88, v130
	v_mul_f32_e32 v89, v89, v130
	v_mul_f32_e32 v90, v90, v130
	v_mul_f32_e32 v91, v91, v130
	v_fmac_f32_e32 v180, v84, v156
	v_fmac_f32_e32 v181, v85, v157
	v_fmac_f32_e32 v182, v86, v158
	v_fmac_f32_e32 v183, v87, v159
	v_fmac_f32_e32 v184, v88, v160
	v_fmac_f32_e32 v185, v89, v161
	v_fmac_f32_e32 v186, v90, v162
	v_fmac_f32_e32 v187, v91, v163
	global_store_dwordx4 v140, v[180:183], s[22:23] offset:512
	global_store_dwordx4 v140, v[184:187], s[22:23] offset:528
	s_add_u32 s22, s20, 0x30000
	s_addc_u32 s23, s21, 0
	v_lshlrev_b32_e32 v164, 16, v212
	v_and_b32_e32 v165, 0xffff0000, v212
	v_lshlrev_b32_e32 v166, 16, v213
	v_and_b32_e32 v167, 0xffff0000, v213
	v_lshlrev_b32_e32 v168, 16, v214
	v_and_b32_e32 v169, 0xffff0000, v214
	v_lshlrev_b32_e32 v170, 16, v215
	v_and_b32_e32 v171, 0xffff0000, v215
	v_mul_f32_e32 v76, v76, v131
	v_mul_f32_e32 v77, v77, v131
	v_mul_f32_e32 v78, v78, v131
	v_mul_f32_e32 v79, v79, v131
	v_mul_f32_e32 v64, v64, v131
	v_mul_f32_e32 v65, v65, v131
	v_mul_f32_e32 v66, v66, v131
	v_mul_f32_e32 v67, v67, v131
	v_fmac_f32_e32 v164, v76, v148
	v_fmac_f32_e32 v165, v77, v149
	v_fmac_f32_e32 v166, v78, v150
	v_fmac_f32_e32 v167, v79, v151
	v_fmac_f32_e32 v168, v64, v152
	v_fmac_f32_e32 v169, v65, v153
	v_fmac_f32_e32 v170, v66, v154
	v_fmac_f32_e32 v171, v67, v155
	global_store_dwordx4 v140, v[164:167], s[22:23]
	global_store_dwordx4 v140, v[168:171], s[22:23] offset:16
	v_lshlrev_b32_e32 v172, 16, v216
	v_and_b32_e32 v173, 0xffff0000, v216
	v_lshlrev_b32_e32 v174, 16, v217
	v_and_b32_e32 v175, 0xffff0000, v217
	v_lshlrev_b32_e32 v176, 16, v218
	v_and_b32_e32 v177, 0xffff0000, v218
	v_lshlrev_b32_e32 v178, 16, v219
	v_and_b32_e32 v179, 0xffff0000, v219
	v_mul_f32_e32 v68, v68, v131
	v_mul_f32_e32 v69, v69, v131
	v_mul_f32_e32 v70, v70, v131
	v_mul_f32_e32 v71, v71, v131
	v_mul_f32_e32 v72, v72, v131
	v_mul_f32_e32 v73, v73, v131
	v_mul_f32_e32 v74, v74, v131
	v_mul_f32_e32 v75, v75, v131
	v_fmac_f32_e32 v172, v68, v156
	v_fmac_f32_e32 v173, v69, v157
	v_fmac_f32_e32 v174, v70, v158
	v_fmac_f32_e32 v175, v71, v159
	v_fmac_f32_e32 v176, v72, v160
	v_fmac_f32_e32 v177, v73, v161
	v_fmac_f32_e32 v178, v74, v162
	v_fmac_f32_e32 v179, v75, v163
	global_store_dwordx4 v140, v[172:175], s[22:23] offset:512
	global_store_dwordx4 v140, v[176:179], s[22:23] offset:528
	s_add_u32 s22, s20, 0x80000
	s_addc_u32 s23, s21, 0
	v_lshlrev_b32_e32 v180, 16, v220
	v_and_b32_e32 v181, 0xffff0000, v220
	v_lshlrev_b32_e32 v182, 16, v221
	v_and_b32_e32 v183, 0xffff0000, v221
	v_lshlrev_b32_e32 v184, 16, v222
	v_and_b32_e32 v185, 0xffff0000, v222
	v_lshlrev_b32_e32 v186, 16, v223
	v_and_b32_e32 v187, 0xffff0000, v223
	v_mul_f32_e32 v60, v60, v132
	v_mul_f32_e32 v61, v61, v132
	v_mul_f32_e32 v62, v62, v132
	v_mul_f32_e32 v63, v63, v132
	v_mul_f32_e32 v48, v48, v132
	v_mul_f32_e32 v49, v49, v132
	v_mul_f32_e32 v50, v50, v132
	v_mul_f32_e32 v51, v51, v132
	v_fmac_f32_e32 v180, v60, v148
	v_fmac_f32_e32 v181, v61, v149
	v_fmac_f32_e32 v182, v62, v150
	v_fmac_f32_e32 v183, v63, v151
	v_fmac_f32_e32 v184, v48, v152
	v_fmac_f32_e32 v185, v49, v153
	v_fmac_f32_e32 v186, v50, v154
	v_fmac_f32_e32 v187, v51, v155
	global_store_dwordx4 v140, v[180:183], s[22:23]
	global_store_dwordx4 v140, v[184:187], s[22:23] offset:16
	v_lshlrev_b32_e32 v164, 16, v224
	v_and_b32_e32 v165, 0xffff0000, v224
	v_lshlrev_b32_e32 v166, 16, v225
	v_and_b32_e32 v167, 0xffff0000, v225
	v_lshlrev_b32_e32 v168, 16, v226
	v_and_b32_e32 v169, 0xffff0000, v226
	v_lshlrev_b32_e32 v170, 16, v227
	v_and_b32_e32 v171, 0xffff0000, v227
	v_mul_f32_e32 v52, v52, v132
	v_mul_f32_e32 v53, v53, v132
	v_mul_f32_e32 v54, v54, v132
	v_mul_f32_e32 v55, v55, v132
	v_mul_f32_e32 v56, v56, v132
	v_mul_f32_e32 v57, v57, v132
	v_mul_f32_e32 v58, v58, v132
	v_mul_f32_e32 v59, v59, v132
	v_fmac_f32_e32 v164, v52, v156
	v_fmac_f32_e32 v165, v53, v157
	v_fmac_f32_e32 v166, v54, v158
	v_fmac_f32_e32 v167, v55, v159
	v_fmac_f32_e32 v168, v56, v160
	v_fmac_f32_e32 v169, v57, v161
	v_fmac_f32_e32 v170, v58, v162
	v_fmac_f32_e32 v171, v59, v163
	global_store_dwordx4 v140, v[164:167], s[22:23] offset:512
	global_store_dwordx4 v140, v[168:171], s[22:23] offset:528
	s_add_u32 s22, s20, 0x90000
	s_addc_u32 s23, s21, 0
	v_lshlrev_b32_e32 v172, 16, v228
	v_and_b32_e32 v173, 0xffff0000, v228
	v_lshlrev_b32_e32 v174, 16, v229
	v_and_b32_e32 v175, 0xffff0000, v229
	v_lshlrev_b32_e32 v176, 16, v230
	v_and_b32_e32 v177, 0xffff0000, v230
	v_lshlrev_b32_e32 v178, 16, v231
	v_and_b32_e32 v179, 0xffff0000, v231
	v_mul_f32_e32 v44, v44, v133
	v_mul_f32_e32 v45, v45, v133
	v_mul_f32_e32 v46, v46, v133
	v_mul_f32_e32 v47, v47, v133
	v_mul_f32_e32 v32, v32, v133
	v_mul_f32_e32 v33, v33, v133
	v_mul_f32_e32 v34, v34, v133
	v_mul_f32_e32 v35, v35, v133
	v_fmac_f32_e32 v172, v44, v148
	v_fmac_f32_e32 v173, v45, v149
	v_fmac_f32_e32 v174, v46, v150
	v_fmac_f32_e32 v175, v47, v151
	v_fmac_f32_e32 v176, v32, v152
	v_fmac_f32_e32 v177, v33, v153
	v_fmac_f32_e32 v178, v34, v154
	v_fmac_f32_e32 v179, v35, v155
	global_store_dwordx4 v140, v[172:175], s[22:23]
	global_store_dwordx4 v140, v[176:179], s[22:23] offset:16
	v_lshlrev_b32_e32 v180, 16, v232
	v_and_b32_e32 v181, 0xffff0000, v232
	v_lshlrev_b32_e32 v182, 16, v233
	v_and_b32_e32 v183, 0xffff0000, v233
	v_lshlrev_b32_e32 v184, 16, v234
	v_and_b32_e32 v185, 0xffff0000, v234
	v_lshlrev_b32_e32 v186, 16, v235
	v_and_b32_e32 v187, 0xffff0000, v235
	v_mul_f32_e32 v36, v36, v133
	v_mul_f32_e32 v37, v37, v133
	v_mul_f32_e32 v38, v38, v133
	v_mul_f32_e32 v39, v39, v133
	v_mul_f32_e32 v40, v40, v133
	v_mul_f32_e32 v41, v41, v133
	v_mul_f32_e32 v42, v42, v133
	v_mul_f32_e32 v43, v43, v133
	v_fmac_f32_e32 v180, v36, v156
	v_fmac_f32_e32 v181, v37, v157
	v_fmac_f32_e32 v182, v38, v158
	v_fmac_f32_e32 v183, v39, v159
	v_fmac_f32_e32 v184, v40, v160
	v_fmac_f32_e32 v185, v41, v161
	v_fmac_f32_e32 v186, v42, v162
	v_fmac_f32_e32 v187, v43, v163
	global_store_dwordx4 v140, v[180:183], s[22:23] offset:512
	global_store_dwordx4 v140, v[184:187], s[22:23] offset:528
	s_add_u32 s22, s20, 0xa0000
	s_addc_u32 s23, s21, 0
	v_lshlrev_b32_e32 v164, 16, v236
	v_and_b32_e32 v165, 0xffff0000, v236
	v_lshlrev_b32_e32 v166, 16, v237
	v_and_b32_e32 v167, 0xffff0000, v237
	v_lshlrev_b32_e32 v168, 16, v238
	v_and_b32_e32 v169, 0xffff0000, v238
	v_lshlrev_b32_e32 v170, 16, v239
	v_and_b32_e32 v171, 0xffff0000, v239
	v_mul_f32_e32 v28, v28, v134
	v_mul_f32_e32 v29, v29, v134
	v_mul_f32_e32 v30, v30, v134
	v_mul_f32_e32 v31, v31, v134
	v_mul_f32_e32 v16, v16, v134
	v_mul_f32_e32 v17, v17, v134
	v_mul_f32_e32 v18, v18, v134
	v_mul_f32_e32 v19, v19, v134
	v_fmac_f32_e32 v164, v28, v148
	v_fmac_f32_e32 v165, v29, v149
	v_fmac_f32_e32 v166, v30, v150
	v_fmac_f32_e32 v167, v31, v151
	v_fmac_f32_e32 v168, v16, v152
	v_fmac_f32_e32 v169, v17, v153
	v_fmac_f32_e32 v170, v18, v154
	v_fmac_f32_e32 v171, v19, v155
	global_store_dwordx4 v140, v[164:167], s[22:23]
	global_store_dwordx4 v140, v[168:171], s[22:23] offset:16
	v_lshlrev_b32_e32 v172, 16, v240
	v_and_b32_e32 v173, 0xffff0000, v240
	v_lshlrev_b32_e32 v174, 16, v241
	v_and_b32_e32 v175, 0xffff0000, v241
	v_lshlrev_b32_e32 v176, 16, v242
	v_and_b32_e32 v177, 0xffff0000, v242
	v_lshlrev_b32_e32 v178, 16, v243
	v_and_b32_e32 v179, 0xffff0000, v243
	v_mul_f32_e32 v20, v20, v134
	v_mul_f32_e32 v21, v21, v134
	v_mul_f32_e32 v22, v22, v134
	v_mul_f32_e32 v23, v23, v134
	v_mul_f32_e32 v24, v24, v134
	v_mul_f32_e32 v25, v25, v134
	v_mul_f32_e32 v26, v26, v134
	v_mul_f32_e32 v27, v27, v134
	v_fmac_f32_e32 v172, v20, v156
	v_fmac_f32_e32 v173, v21, v157
	v_fmac_f32_e32 v174, v22, v158
	v_fmac_f32_e32 v175, v23, v159
	v_fmac_f32_e32 v176, v24, v160
	v_fmac_f32_e32 v177, v25, v161
	v_fmac_f32_e32 v178, v26, v162
	v_fmac_f32_e32 v179, v27, v163
	global_store_dwordx4 v140, v[172:175], s[22:23] offset:512
	global_store_dwordx4 v140, v[176:179], s[22:23] offset:528
	s_add_u32 s22, s20, 0xb0000
	s_addc_u32 s23, s21, 0
	v_lshlrev_b32_e32 v180, 16, v244
	v_and_b32_e32 v181, 0xffff0000, v244
	v_lshlrev_b32_e32 v182, 16, v245
	v_and_b32_e32 v183, 0xffff0000, v245
	v_lshlrev_b32_e32 v184, 16, v246
	v_and_b32_e32 v185, 0xffff0000, v246
	v_lshlrev_b32_e32 v186, 16, v247
	v_and_b32_e32 v187, 0xffff0000, v247
	v_mul_f32_e32 v12, v12, v135
	v_mul_f32_e32 v13, v13, v135
	v_mul_f32_e32 v14, v14, v135
	v_mul_f32_e32 v15, v15, v135
	v_mul_f32_e32 v0, v0, v135
	v_mul_f32_e32 v1, v1, v135
	v_mul_f32_e32 v2, v2, v135
	v_mul_f32_e32 v3, v3, v135
	v_fmac_f32_e32 v180, v12, v148
	v_fmac_f32_e32 v181, v13, v149
	v_fmac_f32_e32 v182, v14, v150
	v_fmac_f32_e32 v183, v15, v151
	v_fmac_f32_e32 v184, v0, v152
	v_fmac_f32_e32 v185, v1, v153
	v_fmac_f32_e32 v186, v2, v154
	v_fmac_f32_e32 v187, v3, v155
	global_store_dwordx4 v140, v[180:183], s[22:23]
	global_store_dwordx4 v140, v[184:187], s[22:23] offset:16
	v_lshlrev_b32_e32 v164, 16, v248
	v_and_b32_e32 v165, 0xffff0000, v248
	v_lshlrev_b32_e32 v166, 16, v249
	v_and_b32_e32 v167, 0xffff0000, v249
	v_lshlrev_b32_e32 v168, 16, v250
	v_and_b32_e32 v169, 0xffff0000, v250
	v_lshlrev_b32_e32 v170, 16, v251
	v_and_b32_e32 v171, 0xffff0000, v251
	v_mul_f32_e32 v4, v4, v135
	v_mul_f32_e32 v5, v5, v135
	v_mul_f32_e32 v6, v6, v135
	v_mul_f32_e32 v7, v7, v135
	v_mul_f32_e32 v8, v8, v135
	v_mul_f32_e32 v9, v9, v135
	v_mul_f32_e32 v10, v10, v135
	v_mul_f32_e32 v11, v11, v135
	v_fmac_f32_e32 v164, v4, v156
	v_fmac_f32_e32 v165, v5, v157
	v_fmac_f32_e32 v166, v6, v158
	v_fmac_f32_e32 v167, v7, v159
	v_fmac_f32_e32 v168, v8, v160
	v_fmac_f32_e32 v169, v9, v161
	v_fmac_f32_e32 v170, v10, v162
	v_fmac_f32_e32 v171, v11, v163
	global_store_dwordx4 v140, v[164:167], s[22:23] offset:512
	global_store_dwordx4 v140, v[168:171], s[22:23] offset:528
	s_addk_i32 s2, 0x400
	s_cmpk_ge_u32 s2, 0x420
	s_cselect_b64 vcc, -1, 0
	s_cbranch_vccnz .LBB0_1475
	v_and_b32_e32 v4, 63, v136
	v_ashrrev_i32_e32 v0, 5, v136
	v_readlane_b32 s4, v253, 3
	v_and_b32_e32 v5, -2, v0
	v_lshlrev_b32_e32 v0, 4, v4
	v_mov_b32_e32 v1, 0
	v_readlane_b32 s5, v253, 4
	s_mov_b64 s[0:1], 0x5000
	v_xor_b32_e32 v6, 32, v137
	v_lshl_add_u64 v[2:3], s[4:5], 0, v[0:1]
	v_lshl_add_u64 v[16:17], v[2:3], 0, s[0:1]
	v_and_b32_e32 v3, 64, v137
	v_add_u32_e32 v3, 64, v3
	v_cmp_lt_i32_e64 s[0:1], v6, v3
	v_readlane_b32 s6, v253, 5
	v_readlane_b32 s7, v253, 6
	v_cndmask_b32_e64 v6, v137, v6, s[0:1]
	v_lshlrev_b32_e32 v29, 2, v6
	v_xor_b32_e32 v6, 16, v137
	v_cmp_lt_i32_e64 s[0:1], v6, v3
	v_readlane_b32 s8, v253, 7
	v_readlane_b32 s9, v253, 8
	v_cndmask_b32_e64 v6, v137, v6, s[0:1]
	v_lshlrev_b32_e32 v50, 2, v6
	v_xor_b32_e32 v6, 8, v137
	v_cmp_lt_i32_e64 s[0:1], v6, v3
	v_readlane_b32 s10, v253, 9
	v_readlane_b32 s11, v253, 10
	v_cndmask_b32_e64 v6, v137, v6, s[0:1]
	v_lshlrev_b32_e32 v51, 2, v6
	v_xor_b32_e32 v6, 4, v137
	v_cmp_lt_i32_e64 s[0:1], v6, v3
	v_readlane_b32 s12, v253, 11
	v_readlane_b32 s13, v253, 12
	v_cndmask_b32_e64 v6, v137, v6, s[0:1]
	v_lshlrev_b32_e32 v52, 2, v6
	v_xor_b32_e32 v6, 2, v137
	v_cmp_lt_i32_e64 s[0:1], v6, v3
	v_readlane_b32 s14, v253, 13
	v_readlane_b32 s15, v253, 14
	v_cndmask_b32_e64 v6, v137, v6, s[0:1]
	v_lshlrev_b32_e32 v53, 2, v6
	v_xor_b32_e32 v6, 1, v137
	v_cmp_lt_i32_e64 s[0:1], v6, v3
	v_readlane_b32 s16, v253, 15
	v_readlane_b32 s17, v253, 16
	v_readlane_b32 s18, v253, 17
	v_readlane_b32 s19, v253, 18
	v_mul_u32_u24_e32 v2, 0x4200, v4
	v_cndmask_b32_e64 v3, v137, v6, s[0:1]
	v_lshlrev_b32_e32 v54, 2, v3
	v_lshlrev_b32_e32 v2, 2, v2
	v_mov_b32_e32 v3, v1
	v_readlane_b32 s4, v254, 52
	v_lshl_add_u64 v[18:19], s[44:45], 0, v[2:3]
	v_lshlrev_b32_e32 v2, 3, v4
	v_readlane_b32 s5, v254, 53
	v_cmp_gt_u32_e32 vcc, 16, v4
	v_lshl_add_u64 v[20:21], s[64:65], 0, v[2:3]
	v_lshl_add_u64 v[22:23], s[58:59], 0, v[2:3]
	v_lshl_add_u64 v[24:25], s[4:5], 0, v[0:1]
	v_lshl_add_u32 v26, s2, 4, v5
	s_lshl_b32 s3, s38, 4
	s_mov_b32 s4, 0x3a800000
	s_mov_b32 s5, 0x800000
	v_mov_b32_e32 v28, 0x358637bd
	v_readlane_b32 s6, v254, 54
	v_readlane_b32 s7, v254, 55
	v_readlane_b32 s8, v254, 56
	v_readlane_b32 s9, v254, 57
	v_readlane_b32 s10, v254, 58
	v_readlane_b32 s11, v254, 59
	v_readlane_b32 s12, v254, 60
	v_readlane_b32 s13, v254, 61
	v_readlane_b32 s14, v254, 62
	v_readlane_b32 s15, v254, 63
	v_readlane_b32 s16, v255, 0
	v_readlane_b32 s17, v255, 1
	v_readlane_b32 s18, v255, 2
	v_readlane_b32 s19, v255, 3
	s_branch .LBB0_1471
